# K-loops: leading wave half skips the pre-barrier lgkmcnt(0) (waits after the barrier); trailing half keeps it
# baseline (speedup 1.0000x reference)
; #define PG8_STAGE(bufoff, gbase, voff) do { _Pragma("unroll") for (int _i = 0; _i < 2; ++_i) \
;         __builtin_amdgcn_global_load_lds((const __attribute__((address_space(1))) unsigned*)((const char*)(gbase) + (voff)[_i]), (LAS unsigned*)(lds + (bufoff) + ldsw + _i * 8192), 16, 0, 0); } while (0)
; #define PG8_LDA(dst, b, h) do { _Pragma("unroll") for (int m = 0; m < 4; ++m) _Pragma("unroll") for (int k = 0; k < 2; ++k) dst[m][k] = *(const LAS bf16x8*)(lds + PG8_SA(b, h) + aoff + m * 2048 + k * 1024); } while (0)
; #define PG8_LDB(dst, b, h) do { _Pragma("unroll") for (int n = 0; n < 2; ++n) _Pragma("unroll") for (int k = 0; k < 2; ++k) dst[n][k] = *(const LAS bf16x8*)(lds + PG8_SB(b, h) + boff + n * 2048 + k * 1024); } while (0)
; #define PG8_MMA(ai, bj, At, Bt) do { __builtin_amdgcn_s_setprio(1); _Pragma("unroll") for (int m = 0; m < 4; ++m) _Pragma("unroll") for (int n = 0; n < 2; ++n) _Pragma("unroll") for (int k = 0; k < 2; ++k) \
;         acc[ai][bj][m][n] = __builtin_amdgcn_mfma_f32_16x16x32_bf16(Bt[n][k], At[m][k], acc[ai][bj][m][n], 0, 0, 0); __builtin_amdgcn_s_setprio(0); } while (0)
; #define PG8_WAIT_V(n) asm volatile("s_waitcnt vmcnt(" #n ")" ::: "memory")
; #define PG8_WAIT_L(n) asm volatile("s_waitcnt lgkmcnt(" #n ")" ::: "memory")
; #define PG8_BAR __builtin_amdgcn_s_barrier()
; #define PG8_SCHED __builtin_amdgcn_sched_barrier(0)
; template <class Epi, class SchedT, bool ALIGN_EPI, bool SP2>
; __device__ __forceinline__ void gemm_phase(LAS unsigned char* lds, const int ldk, const int nt, const SchedT& S, const Epi& E) {
;     ...
;             PG8_LDB(B0, 0, 0); PG8_LDB(B1, 0, 1); PG8_SCHED; PG8_LDA(At, 0, 0); PG8_STAGE(PG8_SA(1, 1), a1 + hstep, voffA);
;             PG8_WAIT_V(8); PG8_WAIT_L(0); PG8_BAR; PG8_MMA(0, 0, At, B0); PG8_MMA(0, 1, At, B1); PG8_BAR; PG8_SCHED;
;             PG8_LDA(At, 0, 1); PG8_STAGE(PG8_SB(0, 0), b2, voffB); PG8_STAGE(PG8_SB(0, 1), b2 + hstepB, voffB); PG8_STAGE(PG8_SA(0, 0), a2, voffA);
;             PG8_WAIT_V(8); PG8_WAIT_L(0); PG8_BAR; PG8_MMA(1, 0, At, B0); PG8_MMA(1, 1, At, B1); PG8_BAR; PG8_SCHED;
;             PG8_LDB(B0, 1, 0); PG8_LDB(B1, 1, 1); PG8_SCHED; PG8_LDA(At, 1, 0); PG8_STAGE(PG8_SA(0, 1), a2 + hstep, voffA);
;             PG8_WAIT_V(8); PG8_WAIT_L(0); PG8_BAR; PG8_MMA(0, 0, At, B0); PG8_MMA(0, 1, At, B1); PG8_BAR; PG8_SCHED;
.LBB0_123:
	s_add_u32 s12, s0, 0xfff80080
	s_addc_u32 s13, s1, -1
	s_add_i32 s34, 0, 0x10000
	s_cmp_eq_u32 s21, 28
	s_cselect_b32 s17, s61, s13
	s_cselect_b32 s16, s60, s12
	v_add_u32_e32 v0, s34, v212
	s_cselect_b32 s13, s31, s19
	s_cselect_b32 s12, s30, s18
	s_add_i32 s38, 0, 0x14000
	s_waitcnt lgkmcnt(0)
	ds_read_b128 v[132:135], v0
	ds_read_b128 v[136:139], v0 offset:1024
	ds_read_b128 v[140:143], v0 offset:2048
	ds_read_b128 v[144:147], v0 offset:3072
	v_add_u32_e32 v0, s38, v212
	ds_read_b128 v[148:151], v0
	ds_read_b128 v[152:155], v0 offset:1024
	ds_read_b128 v[184:187], v0 offset:2048
	ds_read_b128 v[188:191], v0 offset:3072
	v_lshl_add_u64 v[2:3], v[236:237], 0, s[24:25]
	s_mov_b32 m0, s92
	s_nop 0
	global_load_lds_dwordx4 v[2:3], off
	v_lshl_add_u64 v[2:3], v[238:239], 0, s[24:25]
	s_mov_b32 m0, s93
	s_nop 0
	global_load_lds_dwordx4 v[2:3], off
	v_lshl_add_u64 v[2:3], s[0:1], 0, v[180:181]
	s_add_i32 m0, s88, 0xc000
	ds_read_b128 v[192:195], v216
	ds_read_b128 v[196:199], v216 offset:1024
	ds_read_b128 v[200:203], v216 offset:2048
	ds_read_b128 v[204:207], v216 offset:3072
	ds_read_b128 v[218:221], v216 offset:4096
	ds_read_b128 v[222:225], v216 offset:5120
	ds_read_b128 v[226:229], v216 offset:6144
	ds_read_b128 v[230:233], v216 offset:7168
	global_load_lds_dwordx4 v[2:3], off
	v_lshl_add_u64 v[2:3], s[0:1], 0, v[182:183]
	s_add_i32 m0, s88, 0xe000
	s_nop 0
	global_load_lds_dwordx4 v[2:3], off
	s_waitcnt vmcnt(8)
	s_cmp_lg_u64 s[58:59], 0
	s_cbranch_scc1 .Lg0w_p1_0
	s_waitcnt lgkmcnt(0)
.Lg0w_p1_0:
	s_barrier
	s_setprio 1
	s_waitcnt lgkmcnt(0)
	v_mfma_f32_16x16x32_bf16 v[128:131], v[132:135], v[192:195], v[128:131]
	v_mfma_f32_16x16x32_bf16 v[124:127], v[140:143], v[192:195], v[124:127]
	v_mfma_f32_16x16x32_bf16 v[112:115], v[132:135], v[200:203], v[112:115]
	v_mfma_f32_16x16x32_bf16 v[108:111], v[140:143], v[200:203], v[108:111]
	v_mfma_f32_16x16x32_bf16 v[96:99], v[132:135], v[218:221], v[96:99]
	v_mfma_f32_16x16x32_bf16 v[92:95], v[140:143], v[218:221], v[92:95]
	v_mfma_f32_16x16x32_bf16 v[80:83], v[132:135], v[226:229], v[80:83]
	v_mfma_f32_16x16x32_bf16 v[76:79], v[140:143], v[226:229], v[76:79]
	v_mfma_f32_16x16x32_bf16 v[128:131], v[136:139], v[196:199], v[128:131]
	v_mfma_f32_16x16x32_bf16 v[124:127], v[144:147], v[196:199], v[124:127]
	v_mfma_f32_16x16x32_bf16 v[112:115], v[136:139], v[204:207], v[112:115]
	v_mfma_f32_16x16x32_bf16 v[108:111], v[144:147], v[204:207], v[108:111]
	v_mfma_f32_16x16x32_bf16 v[96:99], v[136:139], v[222:225], v[96:99]
	v_mfma_f32_16x16x32_bf16 v[92:95], v[144:147], v[222:225], v[92:95]
	v_mfma_f32_16x16x32_bf16 v[80:83], v[136:139], v[230:233], v[80:83]
	v_mfma_f32_16x16x32_bf16 v[76:79], v[144:147], v[230:233], v[76:79]
	s_setprio 0
	s_setprio 1
	v_mfma_f32_16x16x32_bf16 v[120:123], v[148:151], v[192:195], v[120:123]
	v_mfma_f32_16x16x32_bf16 v[116:119], v[184:187], v[192:195], v[116:119]
	v_mfma_f32_16x16x32_bf16 v[104:107], v[148:151], v[200:203], v[104:107]
	v_mfma_f32_16x16x32_bf16 v[100:103], v[184:187], v[200:203], v[100:103]
	v_mfma_f32_16x16x32_bf16 v[88:91], v[148:151], v[218:221], v[88:91]
	v_mfma_f32_16x16x32_bf16 v[84:87], v[184:187], v[218:221], v[84:87]
	v_mfma_f32_16x16x32_bf16 v[72:75], v[148:151], v[226:229], v[72:75]
	v_mfma_f32_16x16x32_bf16 v[68:71], v[184:187], v[226:229], v[68:71]
	v_mfma_f32_16x16x32_bf16 v[120:123], v[152:155], v[196:199], v[120:123]
	v_mfma_f32_16x16x32_bf16 v[116:119], v[188:191], v[196:199], v[116:119]
	v_mfma_f32_16x16x32_bf16 v[104:107], v[152:155], v[204:207], v[104:107]
	v_mfma_f32_16x16x32_bf16 v[100:103], v[188:191], v[204:207], v[100:103]
	v_mfma_f32_16x16x32_bf16 v[88:91], v[152:155], v[222:225], v[88:91]
	v_mfma_f32_16x16x32_bf16 v[84:87], v[188:191], v[222:225], v[84:87]
	v_mfma_f32_16x16x32_bf16 v[72:75], v[152:155], v[230:233], v[72:75]
	v_mfma_f32_16x16x32_bf16 v[68:71], v[188:191], v[230:233], v[68:71]
	s_setprio 0
	s_barrier
	s_add_i32 s34, s34, s87
	v_lshl_add_u64 v[208:209], s[12:13], 0, v[158:159]
	s_mov_b32 m0, s34
	ds_read_b128 v[192:195], v216 offset:16384
	ds_read_b128 v[196:199], v216 offset:17408
	ds_read_b128 v[200:203], v216 offset:18432
	ds_read_b128 v[204:207], v216 offset:19456
	ds_read_b128 v[218:221], v216 offset:20480
	ds_read_b128 v[222:225], v216 offset:21504
	ds_read_b128 v[226:229], v216 offset:22528
	ds_read_b128 v[230:233], v216 offset:23552
	global_load_lds_dwordx4 v[208:209], off
	s_add_i32 m0, s34, 0x2000
	s_add_u32 s34, s12, 0x20000
	v_lshl_add_u64 v[234:235], s[12:13], 0, v[174:175]
	s_addc_u32 s35, s13, 0
	s_add_i32 s38, s38, s87
	global_load_lds_dwordx4 v[234:235], off
	v_lshl_add_u64 v[2:3], s[34:35], 0, v[158:159]
	s_mov_b32 m0, s38
	v_lshl_add_u64 v[236:237], s[16:17], 0, v[156:157]
	global_load_lds_dwordx4 v[2:3], off
	v_lshl_add_u64 v[2:3], s[34:35], 0, v[174:175]
	s_add_i32 m0, s38, 0x2000
	v_lshl_add_u64 v[238:239], s[16:17], 0, v[160:161]
	global_load_lds_dwordx4 v[2:3], off
	s_waitcnt vmcnt(6)
	s_cmp_lg_u64 s[58:59], 0
	s_cbranch_scc1 .Lg0w_p1_1
	s_waitcnt lgkmcnt(0)
; #define PG8_STAGE(bufoff, gbase, voff) do { _Pragma("unroll") for (int _i = 0; _i < 2; ++_i) \
;         __builtin_amdgcn_global_load_lds((const __attribute__((address_space(1))) unsigned*)((const char*)(gbase) + (voff)[_i]), (LAS unsigned*)(lds + (bufoff) + ldsw + _i * 8192), 16, 0, 0); } while (0)
; #define PG8_LDA(dst, b, h) do { _Pragma("unroll") for (int m = 0; m < 4; ++m) _Pragma("unroll") for (int k = 0; k < 2; ++k) dst[m][k] = *(const LAS bf16x8*)(lds + PG8_SA(b, h) + aoff + m * 2048 + k * 1024); } while (0)
; #define PG8_LDB(dst, b, h) do { _Pragma("unroll") for (int n = 0; n < 2; ++n) _Pragma("unroll") for (int k = 0; k < 2; ++k) dst[n][k] = *(const LAS bf16x8*)(lds + PG8_SB(b, h) + boff + n * 2048 + k * 1024); } while (0)
; #define PG8_MMA(ai, bj, At, Bt) do { __builtin_amdgcn_s_setprio(1); _Pragma("unroll") for (int m = 0; m < 4; ++m) _Pragma("unroll") for (int n = 0; n < 2; ++n) _Pragma("unroll") for (int k = 0; k < 2; ++k) \
;         acc[ai][bj][m][n] = __builtin_amdgcn_mfma_f32_16x16x32_bf16(Bt[n][k], At[m][k], acc[ai][bj][m][n], 0, 0, 0); __builtin_amdgcn_s_setprio(0); } while (0)
; #define PG8_WAIT_V(n) asm volatile("s_waitcnt vmcnt(" #n ")" ::: "memory")
; #define PG8_WAIT_L(n) asm volatile("s_waitcnt lgkmcnt(" #n ")" ::: "memory")
; #define PG8_BAR __builtin_amdgcn_s_barrier()
; #define PG8_SCHED __builtin_amdgcn_sched_barrier(0)
; template <class Epi, class SchedT, bool ALIGN_EPI, bool SP2>
; __device__ __forceinline__ void gemm_phase(LAS unsigned char* lds, const int ldk, const int nt, const SchedT& S, const Epi& E) {
;     ...
;             PG8_WAIT_V(8); PG8_WAIT_L(0); PG8_BAR; PG8_MMA(0, 0, At, B0); PG8_MMA(0, 1, At, B1); PG8_BAR; PG8_SCHED;
;             PG8_LDA(At, 0, 1); PG8_STAGE(PG8_SB(0, 0), b2, voffB); PG8_STAGE(PG8_SB(0, 1), b2 + hstepB, voffB); PG8_STAGE(PG8_SA(0, 0), a2, voffA);
;             PG8_WAIT_V(8); PG8_WAIT_L(0); PG8_BAR; PG8_MMA(1, 0, At, B0); PG8_MMA(1, 1, At, B1); PG8_BAR; PG8_SCHED;
;             PG8_LDB(B0, 1, 0); PG8_LDB(B1, 1, 1); PG8_SCHED; PG8_LDA(At, 1, 0); PG8_STAGE(PG8_SA(0, 1), a2 + hstep, voffA);
;             PG8_WAIT_V(8); PG8_WAIT_L(0); PG8_BAR; PG8_MMA(0, 0, At, B0); PG8_MMA(0, 1, At, B1); PG8_BAR; PG8_SCHED;
.Lg0w_p1_1:
	s_barrier
	s_setprio 1
	s_waitcnt lgkmcnt(0)
	v_mfma_f32_16x16x32_bf16 v[64:67], v[132:135], v[192:195], v[64:67]
	v_mfma_f32_16x16x32_bf16 v[60:63], v[140:143], v[192:195], v[60:63]
	v_mfma_f32_16x16x32_bf16 v[48:51], v[132:135], v[200:203], v[48:51]
	v_mfma_f32_16x16x32_bf16 v[44:47], v[140:143], v[200:203], v[44:47]
	v_mfma_f32_16x16x32_bf16 v[32:35], v[132:135], v[218:221], v[32:35]
	v_mfma_f32_16x16x32_bf16 v[28:31], v[140:143], v[218:221], v[28:31]
	v_mfma_f32_16x16x32_bf16 v[16:19], v[132:135], v[226:229], v[16:19]
	v_mfma_f32_16x16x32_bf16 v[12:15], v[140:143], v[226:229], v[12:15]
	v_mfma_f32_16x16x32_bf16 v[64:67], v[136:139], v[196:199], v[64:67]
	v_mfma_f32_16x16x32_bf16 v[60:63], v[144:147], v[196:199], v[60:63]
	v_mfma_f32_16x16x32_bf16 v[48:51], v[136:139], v[204:207], v[48:51]
	v_mfma_f32_16x16x32_bf16 v[44:47], v[144:147], v[204:207], v[44:47]
	v_mfma_f32_16x16x32_bf16 v[32:35], v[136:139], v[222:225], v[32:35]
	v_mfma_f32_16x16x32_bf16 v[28:31], v[144:147], v[222:225], v[28:31]
	v_mfma_f32_16x16x32_bf16 v[16:19], v[136:139], v[230:233], v[16:19]
	v_mfma_f32_16x16x32_bf16 v[12:15], v[144:147], v[230:233], v[12:15]
	s_setprio 0
	s_setprio 1
	v_mfma_f32_16x16x32_bf16 v[56:59], v[148:151], v[192:195], v[56:59]
	v_mfma_f32_16x16x32_bf16 v[52:55], v[184:187], v[192:195], v[52:55]
	v_mfma_f32_16x16x32_bf16 v[40:43], v[148:151], v[200:203], v[40:43]
	v_mfma_f32_16x16x32_bf16 v[36:39], v[184:187], v[200:203], v[36:39]
	v_mfma_f32_16x16x32_bf16 v[24:27], v[148:151], v[218:221], v[24:27]
	v_mfma_f32_16x16x32_bf16 v[20:23], v[184:187], v[218:221], v[20:23]
	v_mfma_f32_16x16x32_bf16 v[8:11], v[148:151], v[226:229], v[8:11]
	v_mfma_f32_16x16x32_bf16 v[2:5], v[184:187], v[226:229], v[4:7]
	v_mfma_f32_16x16x32_bf16 v[56:59], v[152:155], v[196:199], v[56:59]
	v_mfma_f32_16x16x32_bf16 v[52:55], v[188:191], v[196:199], v[52:55]
	v_mfma_f32_16x16x32_bf16 v[40:43], v[152:155], v[204:207], v[40:43]
	v_mfma_f32_16x16x32_bf16 v[36:39], v[188:191], v[204:207], v[36:39]
	v_mfma_f32_16x16x32_bf16 v[24:27], v[152:155], v[222:225], v[24:27]
	v_mfma_f32_16x16x32_bf16 v[20:23], v[188:191], v[222:225], v[20:23]
	v_mfma_f32_16x16x32_bf16 v[8:11], v[152:155], v[230:233], v[8:11]
	v_mfma_f32_16x16x32_bf16 v[2:5], v[188:191], v[230:233], v[2:5]
	s_setprio 0
	s_barrier
	s_add_i32 s34, 0, 0x18000
	v_add_u32_e32 v0, s34, v212
	s_add_i32 s35, 0, 0x1c000
	ds_read_b128 v[132:135], v0
	ds_read_b128 v[136:139], v0 offset:1024
	ds_read_b128 v[140:143], v0 offset:2048
	ds_read_b128 v[144:147], v0 offset:3072
	v_add_u32_e32 v0, s35, v212
	ds_read_b128 v[148:151], v0
	ds_read_b128 v[152:155], v0 offset:1024
	ds_read_b128 v[184:187], v0 offset:2048
	ds_read_b128 v[188:191], v0 offset:3072
	s_add_u32 s16, s16, 0x80000
	s_addc_u32 s17, s17, 0
	s_mov_b32 m0, s88
	s_nop 0
	global_load_lds_dwordx4 v[236:237], off
	s_mov_b32 m0, s89
	s_nop 0
	global_load_lds_dwordx4 v[238:239], off
	s_mov_b32 m0, s90
	v_lshl_add_u64 v[6:7], s[16:17], 0, v[156:157]
	ds_read_b128 v[192:195], v216 offset:32768
	ds_read_b128 v[196:199], v216 offset:33792
	ds_read_b128 v[200:203], v216 offset:34816
	ds_read_b128 v[204:207], v216 offset:35840
	ds_read_b128 v[218:221], v216 offset:36864
	ds_read_b128 v[222:225], v216 offset:37888
	ds_read_b128 v[226:229], v216 offset:38912
	ds_read_b128 v[230:233], v216 offset:39936
	global_load_lds_dwordx4 v[6:7], off
	v_lshl_add_u64 v[6:7], s[16:17], 0, v[160:161]
	s_mov_b32 m0, s91
	s_nop 0
	global_load_lds_dwordx4 v[6:7], off
	s_nop 0
	s_waitcnt vmcnt(8)
	s_cmp_lg_u64 s[58:59], 0
	s_cbranch_scc1 .Lg0w_p1_2
	s_waitcnt lgkmcnt(0)
; #define PG8_STAGE(bufoff, gbase, voff) do { _Pragma("unroll") for (int _i = 0; _i < 2; ++_i) \
;         __builtin_amdgcn_global_load_lds((const __attribute__((address_space(1))) unsigned*)((const char*)(gbase) + (voff)[_i]), (LAS unsigned*)(lds + (bufoff) + ldsw + _i * 8192), 16, 0, 0); } while (0)
; #define PG8_LDA(dst, b, h) do { _Pragma("unroll") for (int m = 0; m < 4; ++m) _Pragma("unroll") for (int k = 0; k < 2; ++k) dst[m][k] = *(const LAS bf16x8*)(lds + PG8_SA(b, h) + aoff + m * 2048 + k * 1024); } while (0)
; #define PG8_LDB(dst, b, h) do { _Pragma("unroll") for (int n = 0; n < 2; ++n) _Pragma("unroll") for (int k = 0; k < 2; ++k) dst[n][k] = *(const LAS bf16x8*)(lds + PG8_SB(b, h) + boff + n * 2048 + k * 1024); } while (0)
; #define PG8_MMA(ai, bj, At, Bt) do { __builtin_amdgcn_s_setprio(1); _Pragma("unroll") for (int m = 0; m < 4; ++m) _Pragma("unroll") for (int n = 0; n < 2; ++n) _Pragma("unroll") for (int k = 0; k < 2; ++k) \
;         acc[ai][bj][m][n] = __builtin_amdgcn_mfma_f32_16x16x32_bf16(Bt[n][k], At[m][k], acc[ai][bj][m][n], 0, 0, 0); __builtin_amdgcn_s_setprio(0); } while (0)
; #define PG8_WAIT_V(n) asm volatile("s_waitcnt vmcnt(" #n ")" ::: "memory")
; #define PG8_WAIT_L(n) asm volatile("s_waitcnt lgkmcnt(" #n ")" ::: "memory")
; #define PG8_BAR __builtin_amdgcn_s_barrier()
; #define PG8_SCHED __builtin_amdgcn_sched_barrier(0)
; template <class Epi, class SchedT, bool ALIGN_EPI, bool SP2>
; __device__ __forceinline__ void gemm_phase(LAS unsigned char* lds, const int ldk, const int nt, const SchedT& S, const Epi& E) {
;     ...
;             PG8_LDB(B0, 1, 0); PG8_LDB(B1, 1, 1); PG8_SCHED; PG8_LDA(At, 1, 0); PG8_STAGE(PG8_SA(0, 1), a2 + hstep, voffA);
;             PG8_WAIT_V(8); PG8_WAIT_L(0); PG8_BAR; PG8_MMA(0, 0, At, B0); PG8_MMA(0, 1, At, B1); PG8_BAR; PG8_SCHED;
;             PG8_LDA(At, 1, 1); PG8_STAGE(PG8_SB(1, 0), b3, voffB); PG8_STAGE(PG8_SB(1, 1), b3 + hstepB, voffB); PG8_STAGE(PG8_SA(1, 0), a3, voffA);
;             PG8_WAIT_V(8); PG8_WAIT_L(0); PG8_BAR; PG8_MMA(1, 0, At, B0); PG8_MMA(1, 1, At, B1); PG8_BAR; PG8_SCHED;
;     ...
;         if constexpr (ALIGN_EPI) { if (wr == 0) PG8_BAR; }
.Lg0w_p1_2:
	s_barrier
	s_setprio 1
	s_waitcnt lgkmcnt(0)
	v_mfma_f32_16x16x32_bf16 v[128:131], v[132:135], v[192:195], v[128:131]
	v_mfma_f32_16x16x32_bf16 v[124:127], v[140:143], v[192:195], v[124:127]
	v_mfma_f32_16x16x32_bf16 v[112:115], v[132:135], v[200:203], v[112:115]
	v_mfma_f32_16x16x32_bf16 v[108:111], v[140:143], v[200:203], v[108:111]
	v_mfma_f32_16x16x32_bf16 v[96:99], v[132:135], v[218:221], v[96:99]
	v_mfma_f32_16x16x32_bf16 v[92:95], v[140:143], v[218:221], v[92:95]
	v_mfma_f32_16x16x32_bf16 v[80:83], v[132:135], v[226:229], v[80:83]
	v_mfma_f32_16x16x32_bf16 v[76:79], v[140:143], v[226:229], v[76:79]
	v_mfma_f32_16x16x32_bf16 v[128:131], v[136:139], v[196:199], v[128:131]
	v_mfma_f32_16x16x32_bf16 v[124:127], v[144:147], v[196:199], v[124:127]
	v_mfma_f32_16x16x32_bf16 v[112:115], v[136:139], v[204:207], v[112:115]
	v_mfma_f32_16x16x32_bf16 v[108:111], v[144:147], v[204:207], v[108:111]
	v_mfma_f32_16x16x32_bf16 v[96:99], v[136:139], v[222:225], v[96:99]
	v_mfma_f32_16x16x32_bf16 v[92:95], v[144:147], v[222:225], v[92:95]
	v_mfma_f32_16x16x32_bf16 v[80:83], v[136:139], v[230:233], v[80:83]
	v_mfma_f32_16x16x32_bf16 v[76:79], v[144:147], v[230:233], v[76:79]
	s_setprio 0
	s_setprio 1
	v_mfma_f32_16x16x32_bf16 v[120:123], v[148:151], v[192:195], v[120:123]
	v_mfma_f32_16x16x32_bf16 v[116:119], v[184:187], v[192:195], v[116:119]
	v_mfma_f32_16x16x32_bf16 v[104:107], v[148:151], v[200:203], v[104:107]
	v_mfma_f32_16x16x32_bf16 v[100:103], v[184:187], v[200:203], v[100:103]
	v_mfma_f32_16x16x32_bf16 v[88:91], v[148:151], v[218:221], v[88:91]
	v_mfma_f32_16x16x32_bf16 v[84:87], v[184:187], v[218:221], v[84:87]
	v_mfma_f32_16x16x32_bf16 v[72:75], v[148:151], v[226:229], v[72:75]
	v_mfma_f32_16x16x32_bf16 v[68:71], v[184:187], v[226:229], v[68:71]
	v_mfma_f32_16x16x32_bf16 v[120:123], v[152:155], v[196:199], v[120:123]
	v_mfma_f32_16x16x32_bf16 v[116:119], v[188:191], v[196:199], v[116:119]
	v_mfma_f32_16x16x32_bf16 v[104:107], v[152:155], v[204:207], v[104:107]
	v_mfma_f32_16x16x32_bf16 v[100:103], v[188:191], v[204:207], v[100:103]
	v_mfma_f32_16x16x32_bf16 v[88:91], v[152:155], v[222:225], v[88:91]
	v_mfma_f32_16x16x32_bf16 v[84:87], v[188:191], v[222:225], v[84:87]
	v_mfma_f32_16x16x32_bf16 v[72:75], v[152:155], v[230:233], v[72:75]
	v_mfma_f32_16x16x32_bf16 v[68:71], v[188:191], v[230:233], v[68:71]
	s_setprio 0
	s_barrier
	s_add_i32 s16, s34, s87
	v_lshl_add_u64 v[6:7], v[208:209], 0, s[24:25]
	s_mov_b32 m0, s16
	ds_read_b128 v[192:195], v216 offset:49152
	ds_read_b128 v[196:199], v216 offset:50176
	ds_read_b128 v[200:203], v216 offset:51200
	ds_read_b128 v[204:207], v216 offset:52224
	ds_read_b128 v[218:221], v216 offset:53248
	ds_read_b128 v[222:225], v216 offset:54272
	ds_read_b128 v[226:229], v216 offset:55296
	ds_read_b128 v[230:233], v216 offset:56320
	global_load_lds_dwordx4 v[6:7], off
	s_add_i32 m0, s16, 0x2000
	s_add_u32 s12, s12, 0x20080
	v_lshl_add_u64 v[6:7], v[234:235], 0, s[24:25]
	s_addc_u32 s13, s13, 0
	s_add_i32 s16, s35, s87
	global_load_lds_dwordx4 v[6:7], off
	v_lshl_add_u64 v[6:7], s[12:13], 0, v[158:159]
	s_mov_b32 m0, s16
	s_nop 0
	global_load_lds_dwordx4 v[6:7], off
	v_lshl_add_u64 v[6:7], s[12:13], 0, v[174:175]
	s_add_i32 m0, s16, 0x2000
	s_nop 0
	global_load_lds_dwordx4 v[6:7], off
	s_waitcnt vmcnt(6)
	s_cmp_lg_u64 s[58:59], 0
	s_cbranch_scc1 .Lg0w_p1_3
	s_waitcnt lgkmcnt(0)
.Lg0w_p1_3:
	s_barrier
	s_setprio 1
	s_waitcnt lgkmcnt(0)
	v_mfma_f32_16x16x32_bf16 v[64:67], v[132:135], v[192:195], v[64:67]
	v_mfma_f32_16x16x32_bf16 v[60:63], v[140:143], v[192:195], v[60:63]
	v_mfma_f32_16x16x32_bf16 v[48:51], v[132:135], v[200:203], v[48:51]
	v_mfma_f32_16x16x32_bf16 v[44:47], v[140:143], v[200:203], v[44:47]
	v_mfma_f32_16x16x32_bf16 v[32:35], v[132:135], v[218:221], v[32:35]
	v_mfma_f32_16x16x32_bf16 v[28:31], v[140:143], v[218:221], v[28:31]
	v_mfma_f32_16x16x32_bf16 v[16:19], v[132:135], v[226:229], v[16:19]
	v_mfma_f32_16x16x32_bf16 v[12:15], v[140:143], v[226:229], v[12:15]
	v_mfma_f32_16x16x32_bf16 v[64:67], v[136:139], v[196:199], v[64:67]
	v_mfma_f32_16x16x32_bf16 v[60:63], v[144:147], v[196:199], v[60:63]
	v_mfma_f32_16x16x32_bf16 v[48:51], v[136:139], v[204:207], v[48:51]
	v_mfma_f32_16x16x32_bf16 v[44:47], v[144:147], v[204:207], v[44:47]
	v_mfma_f32_16x16x32_bf16 v[32:35], v[136:139], v[222:225], v[32:35]
	v_mfma_f32_16x16x32_bf16 v[28:31], v[144:147], v[222:225], v[28:31]
	v_mfma_f32_16x16x32_bf16 v[16:19], v[136:139], v[230:233], v[16:19]
	v_mfma_f32_16x16x32_bf16 v[12:15], v[144:147], v[230:233], v[12:15]
	s_setprio 0
	s_setprio 1
	v_mfma_f32_16x16x32_bf16 v[56:59], v[148:151], v[192:195], v[56:59]
	v_mfma_f32_16x16x32_bf16 v[52:55], v[184:187], v[192:195], v[52:55]
	v_mfma_f32_16x16x32_bf16 v[40:43], v[148:151], v[200:203], v[40:43]
	v_mfma_f32_16x16x32_bf16 v[36:39], v[184:187], v[200:203], v[36:39]
	v_mfma_f32_16x16x32_bf16 v[24:27], v[148:151], v[218:221], v[24:27]
	v_mfma_f32_16x16x32_bf16 v[20:23], v[184:187], v[218:221], v[20:23]
	v_mfma_f32_16x16x32_bf16 v[6:9], v[148:151], v[226:229], v[8:11]
	v_mfma_f32_16x16x32_bf16 v[2:5], v[184:187], v[226:229], v[2:5]
	v_mfma_f32_16x16x32_bf16 v[56:59], v[152:155], v[196:199], v[56:59]
	v_mfma_f32_16x16x32_bf16 v[52:55], v[188:191], v[196:199], v[52:55]
	v_mfma_f32_16x16x32_bf16 v[40:43], v[152:155], v[204:207], v[40:43]
	v_mfma_f32_16x16x32_bf16 v[36:39], v[188:191], v[204:207], v[36:39]
	v_mfma_f32_16x16x32_bf16 v[24:27], v[152:155], v[222:225], v[24:27]
	v_mfma_f32_16x16x32_bf16 v[20:23], v[188:191], v[222:225], v[20:23]
	v_mfma_f32_16x16x32_bf16 v[8:11], v[152:155], v[230:233], v[6:9]
	v_mfma_f32_16x16x32_bf16 v[4:7], v[188:191], v[230:233], v[2:5]
	s_setprio 0
	s_barrier
	s_add_i32 s21, s21, 2
	s_add_u32 s0, s0, 0x100
	s_addc_u32 s1, s1, 0
	s_add_u32 s18, s18, 0x100
	s_addc_u32 s19, s19, 0
	s_cmp_gt_u32 s21, 29
	s_cbranch_scc0 .LBB0_123
	s_and_b64 vcc, exec, s[58:59]
	s_cbranch_vccz .LBB0_126
	s_barrier

; #define PG8_STAGE(bufoff, gbase, voff) do { _Pragma("unroll") for (int _i = 0; _i < 2; ++_i) \
;         __builtin_amdgcn_global_load_lds((const __attribute__((address_space(1))) unsigned*)((const char*)(gbase) + (voff)[_i]), (LAS unsigned*)(lds + (bufoff) + ldsw + _i * 8192), 16, 0, 0); } while (0)
; #define PG8_LDA(dst, b, h) do { _Pragma("unroll") for (int m = 0; m < 4; ++m) _Pragma("unroll") for (int k = 0; k < 2; ++k) dst[m][k] = *(const LAS bf16x8*)(lds + PG8_SA(b, h) + aoff + m * 2048 + k * 1024); } while (0)
; #define PG8_LDB(dst, b, h) do { _Pragma("unroll") for (int n = 0; n < 2; ++n) _Pragma("unroll") for (int k = 0; k < 2; ++k) dst[n][k] = *(const LAS bf16x8*)(lds + PG8_SB(b, h) + boff + n * 2048 + k * 1024); } while (0)
; #define PG8_MMA(ai, bj, At, Bt) do { __builtin_amdgcn_s_setprio(1); _Pragma("unroll") for (int m = 0; m < 4; ++m) _Pragma("unroll") for (int n = 0; n < 2; ++n) _Pragma("unroll") for (int k = 0; k < 2; ++k) \
;         acc[ai][bj][m][n] = __builtin_amdgcn_mfma_f32_16x16x32_bf16(Bt[n][k], At[m][k], acc[ai][bj][m][n], 0, 0, 0); __builtin_amdgcn_s_setprio(0); } while (0)
; #define PG8_WAIT_V(n) asm volatile("s_waitcnt vmcnt(" #n ")" ::: "memory")
; #define PG8_WAIT_L(n) asm volatile("s_waitcnt lgkmcnt(" #n ")" ::: "memory")
; #define PG8_BAR __builtin_amdgcn_s_barrier()
; template <class Epi, class SchedT, bool ALIGN_EPI, bool SP2>
; __device__ __forceinline__ void gemm_phase(LAS unsigned char* lds, const int ldk, const int nt, const SchedT& S, const Epi& E) {
;     ...
;             const bool last = (t == nt - 2);
;             const char* a1 = cA + (size_t)(t + 1) * kstep;
;             const char* a2 = last ? nA : cA + (size_t)(t + 2) * kstep; const char* b2 = last ? nB : cB + (size_t)(t + 2) * kstep;
;             const char* a3 = a2 + kstep; const char* b3 = b2 + kstep;
;             if constexpr (SP2) {
;             PG8_LDB(B0, 0, 0); PG8_LDB(B1, 0, 1); PG8_SCHED; PG8_LDA(At, 0, 0); PG8_STAGE(PG8_SA(1, 1), a1 + hstep, voffA);
;             PG8_WAIT_V(8); PG8_WAIT_L(0); PG8_BAR; PG8_MMA(0, 0, At, B0); PG8_MMA(0, 1, At, B1); PG8_BAR; PG8_SCHED;
;             PG8_LDA(At, 0, 1); PG8_STAGE(PG8_SB(0, 0), b2, voffB); PG8_STAGE(PG8_SB(0, 1), b2 + hstepB, voffB); PG8_STAGE(PG8_SA(0, 0), a2, voffA);
;             PG8_WAIT_V(8); PG8_WAIT_L(0); PG8_BAR; PG8_MMA(1, 0, At, B0); PG8_MMA(1, 1, At, B1); PG8_BAR; PG8_SCHED;
.LBB0_534:
	s_add_u32 s36, s34, 0xfff80080
	s_addc_u32 s37, s35, -1
	s_add_i32 s49, 0, 0x10000
	s_cmp_eq_u32 s47, 12
	s_cselect_b32 s41, s1, s37
	s_cselect_b32 s40, s0, s36
	v_add_u32_e32 v0, s49, v159
	s_cselect_b32 s37, s53, s20
	s_cselect_b32 s36, s52, s17
	s_add_i32 s51, 0, 0x14000
	ds_read_b128 v[144:147], v0
	ds_read_b128 v[148:151], v0 offset:1024
	ds_read_b128 v[152:155], v0 offset:2048
	ds_read_b128 v[174:177], v0 offset:3072
	v_add_u32_e32 v0, s51, v159
	ds_read_b128 v[178:181], v0
	ds_read_b128 v[182:185], v0 offset:1024
	ds_read_b128 v[186:189], v0 offset:2048
	ds_read_b128 v[190:193], v0 offset:3072
	v_lshl_add_u64 v[2:3], s[34:35], 0, v[140:141]
	s_add_i32 m0, s57, 0xc000
	ds_read_b128 v[194:197], v161
	ds_read_b128 v[198:201], v161 offset:1024
	ds_read_b128 v[202:205], v161 offset:2048
	ds_read_b128 v[206:209], v161 offset:3072
	ds_read_b128 v[210:213], v161 offset:4096
	ds_read_b128 v[214:217], v161 offset:5120
	ds_read_b128 v[218:221], v161 offset:6144
	ds_read_b128 v[222:225], v161 offset:7168
	global_load_lds_dwordx4 v[2:3], off
	v_lshl_add_u64 v[2:3], s[34:35], 0, v[142:143]
	s_add_i32 m0, s57, 0xe000
	s_nop 0
	global_load_lds_dwordx4 v[2:3], off
	s_nop 0
	s_nop 0
	s_waitcnt vmcnt(8)
	s_cmp_lg_u64 s[44:45], 0
	s_cbranch_scc1 .Lg0w_p3_0
	s_waitcnt lgkmcnt(0)
.Lg0w_p3_0:
	s_barrier
	s_setprio 1
	s_waitcnt lgkmcnt(0)
	v_mfma_f32_16x16x32_bf16 v[128:131], v[144:147], v[194:197], v[128:131]
	v_mfma_f32_16x16x32_bf16 v[124:127], v[152:155], v[194:197], v[124:127]
	v_mfma_f32_16x16x32_bf16 v[120:123], v[144:147], v[202:205], v[120:123]
	v_mfma_f32_16x16x32_bf16 v[116:119], v[152:155], v[202:205], v[116:119]
	v_mfma_f32_16x16x32_bf16 v[112:115], v[144:147], v[210:213], v[112:115]
	v_mfma_f32_16x16x32_bf16 v[108:111], v[152:155], v[210:213], v[108:111]
	v_mfma_f32_16x16x32_bf16 v[104:107], v[144:147], v[218:221], v[104:107]
	v_mfma_f32_16x16x32_bf16 v[100:103], v[152:155], v[218:221], v[100:103]
	v_mfma_f32_16x16x32_bf16 v[128:131], v[148:151], v[198:201], v[128:131]
	v_mfma_f32_16x16x32_bf16 v[124:127], v[174:177], v[198:201], v[124:127]
	v_mfma_f32_16x16x32_bf16 v[120:123], v[148:151], v[206:209], v[120:123]
	v_mfma_f32_16x16x32_bf16 v[116:119], v[174:177], v[206:209], v[116:119]
	v_mfma_f32_16x16x32_bf16 v[112:115], v[148:151], v[214:217], v[112:115]
	v_mfma_f32_16x16x32_bf16 v[108:111], v[174:177], v[214:217], v[108:111]
	v_mfma_f32_16x16x32_bf16 v[104:107], v[148:151], v[222:225], v[104:107]
	v_mfma_f32_16x16x32_bf16 v[100:103], v[174:177], v[222:225], v[100:103]
	s_setprio 0
	s_setprio 1
	v_mfma_f32_16x16x32_bf16 v[96:99], v[178:181], v[194:197], v[96:99]
	v_mfma_f32_16x16x32_bf16 v[92:95], v[186:189], v[194:197], v[92:95]
	v_mfma_f32_16x16x32_bf16 v[88:91], v[178:181], v[202:205], v[88:91]
	v_mfma_f32_16x16x32_bf16 v[84:87], v[186:189], v[202:205], v[84:87]
	v_mfma_f32_16x16x32_bf16 v[80:83], v[178:181], v[210:213], v[80:83]
	v_mfma_f32_16x16x32_bf16 v[76:79], v[186:189], v[210:213], v[76:79]
	v_mfma_f32_16x16x32_bf16 v[72:75], v[178:181], v[218:221], v[72:75]
	v_mfma_f32_16x16x32_bf16 v[68:71], v[186:189], v[218:221], v[68:71]
	v_mfma_f32_16x16x32_bf16 v[96:99], v[182:185], v[198:201], v[96:99]
	v_mfma_f32_16x16x32_bf16 v[92:95], v[190:193], v[198:201], v[92:95]
	v_mfma_f32_16x16x32_bf16 v[88:91], v[182:185], v[206:209], v[88:91]
	v_mfma_f32_16x16x32_bf16 v[84:87], v[190:193], v[206:209], v[84:87]
	v_mfma_f32_16x16x32_bf16 v[80:83], v[182:185], v[214:217], v[80:83]
	v_mfma_f32_16x16x32_bf16 v[76:79], v[190:193], v[214:217], v[76:79]
	v_mfma_f32_16x16x32_bf16 v[72:75], v[182:185], v[222:225], v[72:75]
	v_mfma_f32_16x16x32_bf16 v[68:71], v[190:193], v[222:225], v[68:71]
	s_setprio 0
	s_barrier
	s_add_i32 s49, s49, s56
	v_lshl_add_u64 v[156:157], s[36:37], 0, v[134:135]
	s_mov_b32 m0, s49
	ds_read_b128 v[194:197], v161 offset:16384
	ds_read_b128 v[198:201], v161 offset:17408
	ds_read_b128 v[202:205], v161 offset:18432
	ds_read_b128 v[206:209], v161 offset:19456
	ds_read_b128 v[210:213], v161 offset:20480
	ds_read_b128 v[214:217], v161 offset:21504
	ds_read_b128 v[218:221], v161 offset:22528
	ds_read_b128 v[222:225], v161 offset:23552
	global_load_lds_dwordx4 v[156:157], off
	s_add_i32 m0, s49, 0x2000
	s_add_u32 s82, s36, 0x20000
	v_lshl_add_u64 v[226:227], s[36:37], 0, v[138:139]
	s_addc_u32 s83, s37, 0
	s_add_i32 s49, s51, s56
	global_load_lds_dwordx4 v[226:227], off
	v_lshl_add_u64 v[2:3], s[82:83], 0, v[134:135]
	s_mov_b32 m0, s49
	v_lshl_add_u64 v[228:229], s[40:41], 0, v[132:133]
	global_load_lds_dwordx4 v[2:3], off
	v_lshl_add_u64 v[2:3], s[82:83], 0, v[138:139]
	s_add_i32 m0, s49, 0x2000
	v_lshl_add_u64 v[230:231], s[40:41], 0, v[136:137]
	global_load_lds_dwordx4 v[2:3], off
	s_mov_b32 m0, s57
	s_nop 0
	global_load_lds_dwordx4 v[228:229], off
	s_mov_b32 m0, s58
	s_nop 0
	global_load_lds_dwordx4 v[230:231], off
	s_waitcnt vmcnt(8)
	s_cmp_lg_u64 s[44:45], 0
	s_cbranch_scc1 .Lg0w_p3_1
	s_waitcnt lgkmcnt(0)
; #define PG8_STAGE(bufoff, gbase, voff) do { _Pragma("unroll") for (int _i = 0; _i < 2; ++_i) \
;         __builtin_amdgcn_global_load_lds((const __attribute__((address_space(1))) unsigned*)((const char*)(gbase) + (voff)[_i]), (LAS unsigned*)(lds + (bufoff) + ldsw + _i * 8192), 16, 0, 0); } while (0)
; #define PG8_LDA(dst, b, h) do { _Pragma("unroll") for (int m = 0; m < 4; ++m) _Pragma("unroll") for (int k = 0; k < 2; ++k) dst[m][k] = *(const LAS bf16x8*)(lds + PG8_SA(b, h) + aoff + m * 2048 + k * 1024); } while (0)
; #define PG8_LDB(dst, b, h) do { _Pragma("unroll") for (int n = 0; n < 2; ++n) _Pragma("unroll") for (int k = 0; k < 2; ++k) dst[n][k] = *(const LAS bf16x8*)(lds + PG8_SB(b, h) + boff + n * 2048 + k * 1024); } while (0)
; #define PG8_MMA(ai, bj, At, Bt) do { __builtin_amdgcn_s_setprio(1); _Pragma("unroll") for (int m = 0; m < 4; ++m) _Pragma("unroll") for (int n = 0; n < 2; ++n) _Pragma("unroll") for (int k = 0; k < 2; ++k) \
;         acc[ai][bj][m][n] = __builtin_amdgcn_mfma_f32_16x16x32_bf16(Bt[n][k], At[m][k], acc[ai][bj][m][n], 0, 0, 0); __builtin_amdgcn_s_setprio(0); } while (0)
; #define PG8_WAIT_V(n) asm volatile("s_waitcnt vmcnt(" #n ")" ::: "memory")
; #define PG8_WAIT_L(n) asm volatile("s_waitcnt lgkmcnt(" #n ")" ::: "memory")
; #define PG8_BAR __builtin_amdgcn_s_barrier()
; #define PG8_SCHED __builtin_amdgcn_sched_barrier(0)
; template <class Epi, class SchedT, bool ALIGN_EPI, bool SP2>
; __device__ __forceinline__ void gemm_phase(LAS unsigned char* lds, const int ldk, const int nt, const SchedT& S, const Epi& E) {
;     ...
;             PG8_LDA(At, 0, 1); PG8_STAGE(PG8_SB(0, 0), b2, voffB); PG8_STAGE(PG8_SB(0, 1), b2 + hstepB, voffB); PG8_STAGE(PG8_SA(0, 0), a2, voffA);
;             PG8_WAIT_V(8); PG8_WAIT_L(0); PG8_BAR; PG8_MMA(1, 0, At, B0); PG8_MMA(1, 1, At, B1); PG8_BAR; PG8_SCHED;
;             PG8_LDB(B0, 1, 0); PG8_LDB(B1, 1, 1); PG8_SCHED; PG8_LDA(At, 1, 0); PG8_STAGE(PG8_SA(0, 1), a2 + hstep, voffA);
;             PG8_WAIT_V(8); PG8_WAIT_L(0); PG8_BAR; PG8_MMA(0, 0, At, B0); PG8_MMA(0, 1, At, B1); PG8_BAR; PG8_SCHED;
.Lg0w_p3_1:
	s_barrier
	s_setprio 1
	s_waitcnt lgkmcnt(0)
	v_mfma_f32_16x16x32_bf16 v[64:67], v[144:147], v[194:197], v[64:67]
	v_mfma_f32_16x16x32_bf16 v[60:63], v[152:155], v[194:197], v[60:63]
	v_mfma_f32_16x16x32_bf16 v[56:59], v[144:147], v[202:205], v[56:59]
	v_mfma_f32_16x16x32_bf16 v[52:55], v[152:155], v[202:205], v[52:55]
	v_mfma_f32_16x16x32_bf16 v[48:51], v[144:147], v[210:213], v[48:51]
	v_mfma_f32_16x16x32_bf16 v[44:47], v[152:155], v[210:213], v[44:47]
	v_mfma_f32_16x16x32_bf16 v[40:43], v[144:147], v[218:221], v[40:43]
	v_mfma_f32_16x16x32_bf16 v[36:39], v[152:155], v[218:221], v[36:39]
	v_mfma_f32_16x16x32_bf16 v[64:67], v[148:151], v[198:201], v[64:67]
	v_mfma_f32_16x16x32_bf16 v[60:63], v[174:177], v[198:201], v[60:63]
	v_mfma_f32_16x16x32_bf16 v[56:59], v[148:151], v[206:209], v[56:59]
	v_mfma_f32_16x16x32_bf16 v[52:55], v[174:177], v[206:209], v[52:55]
	v_mfma_f32_16x16x32_bf16 v[48:51], v[148:151], v[214:217], v[48:51]
	v_mfma_f32_16x16x32_bf16 v[44:47], v[174:177], v[214:217], v[44:47]
	v_mfma_f32_16x16x32_bf16 v[40:43], v[148:151], v[222:225], v[40:43]
	v_mfma_f32_16x16x32_bf16 v[36:39], v[174:177], v[222:225], v[36:39]
	s_setprio 0
	s_setprio 1
	v_mfma_f32_16x16x32_bf16 v[32:35], v[178:181], v[194:197], v[32:35]
	v_mfma_f32_16x16x32_bf16 v[28:31], v[186:189], v[194:197], v[28:31]
	v_mfma_f32_16x16x32_bf16 v[24:27], v[178:181], v[202:205], v[24:27]
	v_mfma_f32_16x16x32_bf16 v[20:23], v[186:189], v[202:205], v[20:23]
	v_mfma_f32_16x16x32_bf16 v[16:19], v[178:181], v[210:213], v[16:19]
	v_mfma_f32_16x16x32_bf16 v[12:15], v[186:189], v[210:213], v[12:15]
	v_mfma_f32_16x16x32_bf16 v[8:11], v[178:181], v[218:221], v[8:11]
	v_mfma_f32_16x16x32_bf16 v[2:5], v[186:189], v[218:221], v[4:7]
	v_mfma_f32_16x16x32_bf16 v[32:35], v[182:185], v[198:201], v[32:35]
	v_mfma_f32_16x16x32_bf16 v[28:31], v[190:193], v[198:201], v[28:31]
	v_mfma_f32_16x16x32_bf16 v[24:27], v[182:185], v[206:209], v[24:27]
	v_mfma_f32_16x16x32_bf16 v[20:23], v[190:193], v[206:209], v[20:23]
	v_mfma_f32_16x16x32_bf16 v[16:19], v[182:185], v[214:217], v[16:19]
	v_mfma_f32_16x16x32_bf16 v[12:15], v[190:193], v[214:217], v[12:15]
	v_mfma_f32_16x16x32_bf16 v[8:11], v[182:185], v[222:225], v[8:11]
	v_mfma_f32_16x16x32_bf16 v[2:5], v[190:193], v[222:225], v[2:5]
	s_setprio 0
	s_barrier
	s_add_i32 s49, 0, 0x18000
	v_add_u32_e32 v0, s49, v159
	s_add_i32 s51, 0, 0x1c000
	ds_read_b128 v[144:147], v0
	ds_read_b128 v[148:151], v0 offset:1024
	ds_read_b128 v[152:155], v0 offset:2048
	ds_read_b128 v[174:177], v0 offset:3072
	v_add_u32_e32 v0, s51, v159
	ds_read_b128 v[178:181], v0
	ds_read_b128 v[182:185], v0 offset:1024
	ds_read_b128 v[186:189], v0 offset:2048
	ds_read_b128 v[190:193], v0 offset:3072
	s_add_u32 s40, s40, 0x80000
	s_addc_u32 s41, s41, 0
	s_mov_b32 m0, s59
	v_lshl_add_u64 v[6:7], s[40:41], 0, v[132:133]
	ds_read_b128 v[194:197], v161 offset:32768
	ds_read_b128 v[198:201], v161 offset:33792
	ds_read_b128 v[202:205], v161 offset:34816
	ds_read_b128 v[206:209], v161 offset:35840
	ds_read_b128 v[210:213], v161 offset:36864
	ds_read_b128 v[214:217], v161 offset:37888
	ds_read_b128 v[218:221], v161 offset:38912
	ds_read_b128 v[222:225], v161 offset:39936
	global_load_lds_dwordx4 v[6:7], off
	v_lshl_add_u64 v[6:7], s[40:41], 0, v[136:137]
	s_mov_b32 m0, s60
	s_nop 0
	global_load_lds_dwordx4 v[6:7], off
	s_nop 0
	s_waitcnt vmcnt(8)
	s_cmp_lg_u64 s[44:45], 0
	s_cbranch_scc1 .Lg0w_p3_2
	s_waitcnt lgkmcnt(0)
.Lg0w_p3_2:
	s_barrier
	s_setprio 1
	s_waitcnt lgkmcnt(0)
	v_mfma_f32_16x16x32_bf16 v[128:131], v[144:147], v[194:197], v[128:131]
	v_mfma_f32_16x16x32_bf16 v[124:127], v[152:155], v[194:197], v[124:127]
	v_mfma_f32_16x16x32_bf16 v[120:123], v[144:147], v[202:205], v[120:123]
	v_mfma_f32_16x16x32_bf16 v[116:119], v[152:155], v[202:205], v[116:119]
	v_mfma_f32_16x16x32_bf16 v[112:115], v[144:147], v[210:213], v[112:115]
	v_mfma_f32_16x16x32_bf16 v[108:111], v[152:155], v[210:213], v[108:111]
	v_mfma_f32_16x16x32_bf16 v[104:107], v[144:147], v[218:221], v[104:107]
	v_mfma_f32_16x16x32_bf16 v[100:103], v[152:155], v[218:221], v[100:103]
	v_mfma_f32_16x16x32_bf16 v[128:131], v[148:151], v[198:201], v[128:131]
	v_mfma_f32_16x16x32_bf16 v[124:127], v[174:177], v[198:201], v[124:127]
	v_mfma_f32_16x16x32_bf16 v[120:123], v[148:151], v[206:209], v[120:123]
	v_mfma_f32_16x16x32_bf16 v[116:119], v[174:177], v[206:209], v[116:119]
	v_mfma_f32_16x16x32_bf16 v[112:115], v[148:151], v[214:217], v[112:115]
	v_mfma_f32_16x16x32_bf16 v[108:111], v[174:177], v[214:217], v[108:111]
	v_mfma_f32_16x16x32_bf16 v[104:107], v[148:151], v[222:225], v[104:107]
	v_mfma_f32_16x16x32_bf16 v[100:103], v[174:177], v[222:225], v[100:103]
	s_setprio 0
	s_setprio 1
	v_mfma_f32_16x16x32_bf16 v[96:99], v[178:181], v[194:197], v[96:99]
	v_mfma_f32_16x16x32_bf16 v[92:95], v[186:189], v[194:197], v[92:95]
	v_mfma_f32_16x16x32_bf16 v[88:91], v[178:181], v[202:205], v[88:91]
	v_mfma_f32_16x16x32_bf16 v[84:87], v[186:189], v[202:205], v[84:87]
	v_mfma_f32_16x16x32_bf16 v[80:83], v[178:181], v[210:213], v[80:83]
	v_mfma_f32_16x16x32_bf16 v[76:79], v[186:189], v[210:213], v[76:79]
	v_mfma_f32_16x16x32_bf16 v[72:75], v[178:181], v[218:221], v[72:75]
	v_mfma_f32_16x16x32_bf16 v[68:71], v[186:189], v[218:221], v[68:71]
	v_mfma_f32_16x16x32_bf16 v[96:99], v[182:185], v[198:201], v[96:99]
	v_mfma_f32_16x16x32_bf16 v[92:95], v[190:193], v[198:201], v[92:95]
	v_mfma_f32_16x16x32_bf16 v[88:91], v[182:185], v[206:209], v[88:91]
	v_mfma_f32_16x16x32_bf16 v[84:87], v[190:193], v[206:209], v[84:87]
	v_mfma_f32_16x16x32_bf16 v[80:83], v[182:185], v[214:217], v[80:83]
	v_mfma_f32_16x16x32_bf16 v[76:79], v[190:193], v[214:217], v[76:79]
	v_mfma_f32_16x16x32_bf16 v[72:75], v[182:185], v[222:225], v[72:75]
	v_mfma_f32_16x16x32_bf16 v[68:71], v[190:193], v[222:225], v[68:71]
	s_setprio 0
	s_barrier
; #define PG8_STAGE(bufoff, gbase, voff) do { _Pragma("unroll") for (int _i = 0; _i < 2; ++_i) \
;         __builtin_amdgcn_global_load_lds((const __attribute__((address_space(1))) unsigned*)((const char*)(gbase) + (voff)[_i]), (LAS unsigned*)(lds + (bufoff) + ldsw + _i * 8192), 16, 0, 0); } while (0)
; #define PG8_LDA(dst, b, h) do { _Pragma("unroll") for (int m = 0; m < 4; ++m) _Pragma("unroll") for (int k = 0; k < 2; ++k) dst[m][k] = *(const LAS bf16x8*)(lds + PG8_SA(b, h) + aoff + m * 2048 + k * 1024); } while (0)
; #define PG8_MMA(ai, bj, At, Bt) do { __builtin_amdgcn_s_setprio(1); _Pragma("unroll") for (int m = 0; m < 4; ++m) _Pragma("unroll") for (int n = 0; n < 2; ++n) _Pragma("unroll") for (int k = 0; k < 2; ++k) \
;         acc[ai][bj][m][n] = __builtin_amdgcn_mfma_f32_16x16x32_bf16(Bt[n][k], At[m][k], acc[ai][bj][m][n], 0, 0, 0); __builtin_amdgcn_s_setprio(0); } while (0)
; #define PG8_WAIT_V(n) asm volatile("s_waitcnt vmcnt(" #n ")" ::: "memory")
; #define PG8_WAIT_L(n) asm volatile("s_waitcnt lgkmcnt(" #n ")" ::: "memory")
; template <class Epi, class SchedT, bool ALIGN_EPI, bool SP2>
; __device__ __forceinline__ void gemm_phase(LAS unsigned char* lds, const int ldk, const int nt, const SchedT& S, const Epi& E) {
;     ...
;             PG8_LDA(At, 1, 1); PG8_STAGE(PG8_SB(1, 0), b3, voffB); PG8_STAGE(PG8_SB(1, 1), b3 + hstepB, voffB); PG8_STAGE(PG8_SA(1, 0), a3, voffA);
;             PG8_WAIT_V(8); PG8_WAIT_L(0); PG8_BAR; PG8_MMA(1, 0, At, B0); PG8_MMA(1, 1, At, B1); PG8_BAR; PG8_SCHED;
;     __device__ __forceinline__ void operator()(f32x4 (&acc)[2][2][4][2], const Unit& u, int wr, int wc, int fr, int fq) const {
;         const int row0 = u.pm * BM + wr * 64 + fr, col0 = u.pn * BM + wc * 64 + 8 * fq;
; #pragma unroll
;         for (int ai = 0; ai < 2; ++ai)
; #pragma unroll
;             for (int m = 0; m < 4; ++m) {
;                 const int row = row0 + ai * HALF + m * 16;
; #pragma unroll
;                 for (int bj = 0; bj < 2; ++bj) {
;                     const int col = col0 + bj * 32;
;                     const unsigned char* grow = (const unsigned char*)Gt + (size_t)row * 4096 + col;
;                     const u32x2 gw = *(const u32x2*)(grow + 2048);
;                     f32x4 g0 = gate_d4(gw.x), g1 = gate_d4(gw.y);
;                     if (u.kind == 0) {
;                         const u32x2 aw = *(const u32x2*)grow;
	s_add_i32 s40, s49, s56
	v_lshl_add_u64 v[6:7], v[156:157], 0, s[24:25]
	s_mov_b32 m0, s40
	ds_read_b128 v[194:197], v161 offset:49152
	ds_read_b128 v[198:201], v161 offset:50176
	ds_read_b128 v[202:205], v161 offset:51200
	ds_read_b128 v[206:209], v161 offset:52224
	ds_read_b128 v[210:213], v161 offset:53248
	ds_read_b128 v[214:217], v161 offset:54272
	ds_read_b128 v[218:221], v161 offset:55296
	ds_read_b128 v[222:225], v161 offset:56320
	global_load_lds_dwordx4 v[6:7], off
	s_add_i32 m0, s40, 0x2000
	s_add_u32 s36, s36, 0x20080
	v_lshl_add_u64 v[6:7], v[226:227], 0, s[24:25]
	s_addc_u32 s37, s37, 0
	s_add_i32 s40, s51, s56
	global_load_lds_dwordx4 v[6:7], off
	v_lshl_add_u64 v[6:7], s[36:37], 0, v[134:135]
	s_mov_b32 m0, s40
	s_nop 0
	global_load_lds_dwordx4 v[6:7], off
	v_lshl_add_u64 v[6:7], s[36:37], 0, v[138:139]
	s_add_i32 m0, s40, 0x2000
	s_nop 0
	global_load_lds_dwordx4 v[6:7], off
	v_lshl_add_u64 v[6:7], v[228:229], 0, s[24:25]
	s_mov_b32 m0, s61
	s_nop 0
	global_load_lds_dwordx4 v[6:7], off
	v_lshl_add_u64 v[6:7], v[230:231], 0, s[24:25]
	s_mov_b32 m0, s62
	s_nop 0
	global_load_lds_dwordx4 v[6:7], off
	s_waitcnt vmcnt(8)
	s_cmp_lg_u64 s[44:45], 0
	s_cbranch_scc1 .Lg0w_p3_3
	s_waitcnt lgkmcnt(0)
.Lg0w_p3_3:
	s_barrier
	s_setprio 1
	s_waitcnt lgkmcnt(0)
	v_mfma_f32_16x16x32_bf16 v[64:67], v[144:147], v[194:197], v[64:67]
	v_mfma_f32_16x16x32_bf16 v[60:63], v[152:155], v[194:197], v[60:63]
	v_mfma_f32_16x16x32_bf16 v[56:59], v[144:147], v[202:205], v[56:59]
	v_mfma_f32_16x16x32_bf16 v[52:55], v[152:155], v[202:205], v[52:55]
	v_mfma_f32_16x16x32_bf16 v[48:51], v[144:147], v[210:213], v[48:51]
	v_mfma_f32_16x16x32_bf16 v[44:47], v[152:155], v[210:213], v[44:47]
	v_mfma_f32_16x16x32_bf16 v[40:43], v[144:147], v[218:221], v[40:43]
	v_mfma_f32_16x16x32_bf16 v[36:39], v[152:155], v[218:221], v[36:39]
	v_mfma_f32_16x16x32_bf16 v[64:67], v[148:151], v[198:201], v[64:67]
	v_mfma_f32_16x16x32_bf16 v[60:63], v[174:177], v[198:201], v[60:63]
	v_mfma_f32_16x16x32_bf16 v[56:59], v[148:151], v[206:209], v[56:59]
	v_mfma_f32_16x16x32_bf16 v[52:55], v[174:177], v[206:209], v[52:55]
	v_mfma_f32_16x16x32_bf16 v[48:51], v[148:151], v[214:217], v[48:51]
	v_mfma_f32_16x16x32_bf16 v[44:47], v[174:177], v[214:217], v[44:47]
	v_mfma_f32_16x16x32_bf16 v[40:43], v[148:151], v[222:225], v[40:43]
	v_mfma_f32_16x16x32_bf16 v[36:39], v[174:177], v[222:225], v[36:39]
	s_setprio 0
	s_setprio 1
	v_mfma_f32_16x16x32_bf16 v[32:35], v[178:181], v[194:197], v[32:35]
	v_mfma_f32_16x16x32_bf16 v[28:31], v[186:189], v[194:197], v[28:31]
	v_mfma_f32_16x16x32_bf16 v[24:27], v[178:181], v[202:205], v[24:27]
	v_mfma_f32_16x16x32_bf16 v[20:23], v[186:189], v[202:205], v[20:23]
	v_mfma_f32_16x16x32_bf16 v[16:19], v[178:181], v[210:213], v[16:19]
	v_mfma_f32_16x16x32_bf16 v[12:15], v[186:189], v[210:213], v[12:15]
	v_mfma_f32_16x16x32_bf16 v[6:9], v[178:181], v[218:221], v[8:11]
	v_mfma_f32_16x16x32_bf16 v[2:5], v[186:189], v[218:221], v[2:5]
	v_mfma_f32_16x16x32_bf16 v[32:35], v[182:185], v[198:201], v[32:35]
	v_mfma_f32_16x16x32_bf16 v[28:31], v[190:193], v[198:201], v[28:31]
	v_mfma_f32_16x16x32_bf16 v[24:27], v[182:185], v[206:209], v[24:27]
	v_mfma_f32_16x16x32_bf16 v[20:23], v[190:193], v[206:209], v[20:23]
	v_mfma_f32_16x16x32_bf16 v[16:19], v[182:185], v[214:217], v[16:19]
	v_mfma_f32_16x16x32_bf16 v[12:15], v[190:193], v[214:217], v[12:15]
	v_mfma_f32_16x16x32_bf16 v[8:11], v[182:185], v[222:225], v[6:9]
	v_mfma_f32_16x16x32_bf16 v[4:7], v[190:193], v[222:225], v[2:5]
	s_setprio 0
	s_barrier
	s_add_i32 s47, s47, 2
	s_add_u32 s34, s34, 0x100
	s_addc_u32 s35, s35, 0
	s_add_u32 s17, s17, 0x100
	s_addc_u32 s20, s20, 0
	s_cmp_gt_u32 s47, 13
	s_cbranch_scc0 .LBB0_534
	v_lshl_add_u32 v144, s16, 8, v158
	v_lshl_or_b32 v145, s12, 8, v160
	v_lshl_add_u32 v146, v144, 12, v145
	v_add_u32_e32 v147, 0x10000, v146
	v_add_u32_e32 v148, 0x20000, v146
	v_add_u32_e32 v149, 0x30000, v146
	v_add_u32_e32 v150, 0x80000, v146
	v_add_u32_e32 v151, 0x90000, v146
	v_add_u32_e32 v152, 0xa0000, v146
	v_add_u32_e32 v153, 0xb0000, v146
	s_cmp_lg_u32 s13, 0
	s_cbranch_scc1 .Lp3e_k1_loads
	global_load_dwordx2 v[174:175], v146, s[30:31] offset:2048
	global_load_dwordx2 v[176:177], v146, s[30:31] offset:0
	global_load_dwordx2 v[178:179], v146, s[30:31] offset:2080
	global_load_dwordx2 v[180:181], v146, s[30:31] offset:32
	global_load_dwordx2 v[182:183], v147, s[30:31] offset:2048
	global_load_dwordx2 v[184:185], v147, s[30:31] offset:0
	global_load_dwordx2 v[186:187], v147, s[30:31] offset:2080
	global_load_dwordx2 v[188:189], v147, s[30:31] offset:32
	global_load_dwordx2 v[190:191], v148, s[30:31] offset:2048
	global_load_dwordx2 v[192:193], v148, s[30:31] offset:0
	global_load_dwordx2 v[194:195], v148, s[30:31] offset:2080
	global_load_dwordx2 v[196:197], v148, s[30:31] offset:32
	global_load_dwordx2 v[198:199], v149, s[30:31] offset:2048
	global_load_dwordx2 v[200:201], v149, s[30:31] offset:0
	global_load_dwordx2 v[202:203], v149, s[30:31] offset:2080
	global_load_dwordx2 v[204:205], v149, s[30:31] offset:32
	global_load_dwordx2 v[206:207], v150, s[30:31] offset:2048
	global_load_dwordx2 v[208:209], v150, s[30:31] offset:0
	global_load_dwordx2 v[210:211], v150, s[30:31] offset:2080
	global_load_dwordx2 v[212:213], v150, s[30:31] offset:32
	global_load_dwordx2 v[214:215], v151, s[30:31] offset:2048
	global_load_dwordx2 v[216:217], v151, s[30:31] offset:0
	global_load_dwordx2 v[218:219], v151, s[30:31] offset:2080
	global_load_dwordx2 v[220:221], v151, s[30:31] offset:32
	global_load_dwordx2 v[222:223], v152, s[30:31] offset:2048
	global_load_dwordx2 v[224:225], v152, s[30:31] offset:0
	global_load_dwordx2 v[226:227], v152, s[30:31] offset:2080
	global_load_dwordx2 v[228:229], v152, s[30:31] offset:32
	global_load_dwordx2 v[230:231], v153, s[30:31] offset:2048
	global_load_dwordx2 v[232:233], v153, s[30:31] offset:0
	global_load_dwordx2 v[234:235], v153, s[30:31] offset:2080
	global_load_dwordx2 v[236:237], v153, s[30:31] offset:32
	s_branch .Lp3e_align

; #define PG8_STAGE(bufoff, gbase, voff) do { _Pragma("unroll") for (int _i = 0; _i < 2; ++_i) \
;         __builtin_amdgcn_global_load_lds((const __attribute__((address_space(1))) unsigned*)((const char*)(gbase) + (voff)[_i]), (LAS unsigned*)(lds + (bufoff) + ldsw + _i * 8192), 16, 0, 0); } while (0)
; #define PG8_LDA(dst, b, h) do { _Pragma("unroll") for (int m = 0; m < 4; ++m) _Pragma("unroll") for (int k = 0; k < 2; ++k) dst[m][k] = *(const LAS bf16x8*)(lds + PG8_SA(b, h) + aoff + m * 2048 + k * 1024); } while (0)
; #define PG8_LDB(dst, b, h) do { _Pragma("unroll") for (int n = 0; n < 2; ++n) _Pragma("unroll") for (int k = 0; k < 2; ++k) dst[n][k] = *(const LAS bf16x8*)(lds + PG8_SB(b, h) + boff + n * 2048 + k * 1024); } while (0)
; #define PG8_MMA(ai, bj, At, Bt) do { __builtin_amdgcn_s_setprio(1); _Pragma("unroll") for (int m = 0; m < 4; ++m) _Pragma("unroll") for (int n = 0; n < 2; ++n) _Pragma("unroll") for (int k = 0; k < 2; ++k) \
;         acc[ai][bj][m][n] = __builtin_amdgcn_mfma_f32_16x16x32_bf16(Bt[n][k], At[m][k], acc[ai][bj][m][n], 0, 0, 0); __builtin_amdgcn_s_setprio(0); } while (0)
; #define PG8_WAIT_V(n) asm volatile("s_waitcnt vmcnt(" #n ")" ::: "memory")
; #define PG8_WAIT_L(n) asm volatile("s_waitcnt lgkmcnt(" #n ")" ::: "memory")
; #define PG8_BAR __builtin_amdgcn_s_barrier()
; template <class Epi, class SchedT, bool ALIGN_EPI, bool SP2>
; __device__ __forceinline__ void gemm_phase(LAS unsigned char* lds, const int ldk, const int nt, const SchedT& S, const Epi& E) {
;     ...
;             const bool last = (t == nt - 2);
;             const char* a1 = cA + (size_t)(t + 1) * kstep;
;             const char* a2 = last ? nA : cA + (size_t)(t + 2) * kstep; const char* b2 = last ? nB : cB + (size_t)(t + 2) * kstep;
;             const char* a3 = a2 + kstep; const char* b3 = b2 + kstep;
;             if constexpr (SP2) {
;             PG8_LDB(B0, 0, 0); PG8_LDB(B1, 0, 1); PG8_SCHED; PG8_LDA(At, 0, 0); PG8_STAGE(PG8_SA(1, 1), a1 + hstep, voffA);
;             PG8_WAIT_V(8); PG8_WAIT_L(0); PG8_BAR; PG8_MMA(0, 0, At, B0); PG8_MMA(0, 1, At, B1); PG8_BAR; PG8_SCHED;
;             PG8_LDA(At, 0, 1); PG8_STAGE(PG8_SB(0, 0), b2, voffB); PG8_STAGE(PG8_SB(0, 1), b2 + hstepB, voffB); PG8_STAGE(PG8_SA(0, 0), a2, voffA);
;             PG8_WAIT_V(8); PG8_WAIT_L(0); PG8_BAR; PG8_MMA(1, 0, At, B0); PG8_MMA(1, 1, At, B1); PG8_BAR; PG8_SCHED;
.LBB0_668:
	s_add_u32 s36, s34, 0xfff80080
	s_addc_u32 s37, s35, -1
	s_add_i32 s51, 0, 0x10000
	s_cmp_eq_u32 s22, 28
	s_cselect_b32 s57, s1, s37
	s_cselect_b32 s56, s0, s36
	v_add_u32_e32 v144, s51, v147
	s_cselect_b32 s37, s55, s20
	s_cselect_b32 s36, s54, s13
	s_add_i32 s53, 0, 0x14000
	ds_read_b128 v[140:143], v144
	ds_read_b128 v[150:153], v144 offset:1024
	ds_read_b128 v[154:157], v144 offset:2048
	ds_read_b128 v[158:161], v144 offset:3072
	v_add_u32_e32 v144, s53, v147
	ds_read_b128 v[174:177], v144
	ds_read_b128 v[178:181], v144 offset:1024
	ds_read_b128 v[182:185], v144 offset:2048
	ds_read_b128 v[186:189], v144 offset:3072
	v_lshl_add_u64 v[144:145], s[34:35], 0, v[136:137]
	s_add_i32 m0, s17, 0xc000
	ds_read_b128 v[190:193], v149
	ds_read_b128 v[194:197], v149 offset:1024
	ds_read_b128 v[198:201], v149 offset:2048
	ds_read_b128 v[202:205], v149 offset:3072
	ds_read_b128 v[206:209], v149 offset:4096
	ds_read_b128 v[210:213], v149 offset:5120
	ds_read_b128 v[214:217], v149 offset:6144
	ds_read_b128 v[218:221], v149 offset:7168
	global_load_lds_dwordx4 v[144:145], off
	v_lshl_add_u64 v[144:145], s[34:35], 0, v[138:139]
	s_add_i32 m0, s17, 0xe000
	s_nop 0
	global_load_lds_dwordx4 v[144:145], off
	s_nop 0
	s_nop 0
	s_nop 0
	s_waitcnt vmcnt(8)
	s_cmp_lg_u64 s[48:49], 0
	s_cbranch_scc1 .Lg0w_p4_0
	s_waitcnt lgkmcnt(0)
.Lg0w_p4_0:
	s_barrier
	s_setprio 1
	s_waitcnt lgkmcnt(0)
	v_mfma_f32_16x16x32_bf16 v[126:129], v[140:143], v[190:193], v[126:129]
	v_mfma_f32_16x16x32_bf16 v[122:125], v[154:157], v[190:193], v[122:125]
	v_mfma_f32_16x16x32_bf16 v[110:113], v[140:143], v[198:201], v[110:113]
	v_mfma_f32_16x16x32_bf16 v[106:109], v[154:157], v[198:201], v[106:109]
	v_mfma_f32_16x16x32_bf16 v[94:97], v[140:143], v[206:209], v[94:97]
	v_mfma_f32_16x16x32_bf16 v[90:93], v[154:157], v[206:209], v[90:93]
	v_mfma_f32_16x16x32_bf16 v[78:81], v[140:143], v[214:217], v[78:81]
	v_mfma_f32_16x16x32_bf16 v[74:77], v[154:157], v[214:217], v[74:77]
	v_mfma_f32_16x16x32_bf16 v[126:129], v[150:153], v[194:197], v[126:129]
	v_mfma_f32_16x16x32_bf16 v[122:125], v[158:161], v[194:197], v[122:125]
	v_mfma_f32_16x16x32_bf16 v[110:113], v[150:153], v[202:205], v[110:113]
	v_mfma_f32_16x16x32_bf16 v[106:109], v[158:161], v[202:205], v[106:109]
	v_mfma_f32_16x16x32_bf16 v[94:97], v[150:153], v[210:213], v[94:97]
	v_mfma_f32_16x16x32_bf16 v[90:93], v[158:161], v[210:213], v[90:93]
	v_mfma_f32_16x16x32_bf16 v[78:81], v[150:153], v[218:221], v[78:81]
	v_mfma_f32_16x16x32_bf16 v[74:77], v[158:161], v[218:221], v[74:77]
	s_setprio 0
	s_setprio 1
	v_mfma_f32_16x16x32_bf16 v[118:121], v[174:177], v[190:193], v[118:121]
	v_mfma_f32_16x16x32_bf16 v[114:117], v[182:185], v[190:193], v[114:117]
	v_mfma_f32_16x16x32_bf16 v[102:105], v[174:177], v[198:201], v[102:105]
	v_mfma_f32_16x16x32_bf16 v[98:101], v[182:185], v[198:201], v[98:101]
	v_mfma_f32_16x16x32_bf16 v[86:89], v[174:177], v[206:209], v[86:89]
	v_mfma_f32_16x16x32_bf16 v[82:85], v[182:185], v[206:209], v[82:85]
	v_mfma_f32_16x16x32_bf16 v[70:73], v[174:177], v[214:217], v[70:73]
	v_mfma_f32_16x16x32_bf16 v[66:69], v[182:185], v[214:217], v[66:69]
	v_mfma_f32_16x16x32_bf16 v[118:121], v[178:181], v[194:197], v[118:121]
	v_mfma_f32_16x16x32_bf16 v[114:117], v[186:189], v[194:197], v[114:117]
	v_mfma_f32_16x16x32_bf16 v[102:105], v[178:181], v[202:205], v[102:105]
	v_mfma_f32_16x16x32_bf16 v[98:101], v[186:189], v[202:205], v[98:101]
	v_mfma_f32_16x16x32_bf16 v[86:89], v[178:181], v[210:213], v[86:89]
	v_mfma_f32_16x16x32_bf16 v[82:85], v[186:189], v[210:213], v[82:85]
	v_mfma_f32_16x16x32_bf16 v[70:73], v[178:181], v[218:221], v[70:73]
	v_mfma_f32_16x16x32_bf16 v[66:69], v[186:189], v[218:221], v[66:69]
	s_setprio 0
	s_barrier
	s_add_i32 s51, s51, s61
	v_lshl_add_u64 v[144:145], s[36:37], 0, v[0:1]
	s_mov_b32 m0, s51
	ds_read_b128 v[190:193], v149 offset:16384
	ds_read_b128 v[194:197], v149 offset:17408
	ds_read_b128 v[198:201], v149 offset:18432
	ds_read_b128 v[202:205], v149 offset:19456
	ds_read_b128 v[206:209], v149 offset:20480
	ds_read_b128 v[210:213], v149 offset:21504
	ds_read_b128 v[214:217], v149 offset:22528
	ds_read_b128 v[218:221], v149 offset:23552
	global_load_lds_dwordx4 v[144:145], off
	s_add_i32 m0, s51, 0x2000
	s_add_u32 s86, s36, 0x20000
	v_lshl_add_u64 v[222:223], s[36:37], 0, v[134:135]
	s_addc_u32 s87, s37, 0
	s_add_i32 s51, s53, s61
	global_load_lds_dwordx4 v[222:223], off
	v_lshl_add_u64 v[224:225], s[86:87], 0, v[0:1]
	s_mov_b32 m0, s51
	v_lshl_add_u64 v[226:227], s[56:57], 0, v[132:133]
	global_load_lds_dwordx4 v[224:225], off
	v_lshl_add_u64 v[224:225], s[86:87], 0, v[134:135]
	s_add_i32 m0, s51, 0x2000
	s_nop 0
	global_load_lds_dwordx4 v[224:225], off
	v_lshl_add_u64 v[224:225], s[56:57], 0, v[130:131]
	s_mov_b32 m0, s17
	s_nop 0
	global_load_lds_dwordx4 v[224:225], off
	s_mov_b32 m0, s62
	s_nop 0
	global_load_lds_dwordx4 v[226:227], off
	s_nop 0
	s_waitcnt vmcnt(8)
	s_cmp_lg_u64 s[48:49], 0
	s_cbranch_scc1 .Lg0w_p4_1
	s_waitcnt lgkmcnt(0)
; #define PG8_STAGE(bufoff, gbase, voff) do { _Pragma("unroll") for (int _i = 0; _i < 2; ++_i) \
;         __builtin_amdgcn_global_load_lds((const __attribute__((address_space(1))) unsigned*)((const char*)(gbase) + (voff)[_i]), (LAS unsigned*)(lds + (bufoff) + ldsw + _i * 8192), 16, 0, 0); } while (0)
; #define PG8_LDA(dst, b, h) do { _Pragma("unroll") for (int m = 0; m < 4; ++m) _Pragma("unroll") for (int k = 0; k < 2; ++k) dst[m][k] = *(const LAS bf16x8*)(lds + PG8_SA(b, h) + aoff + m * 2048 + k * 1024); } while (0)
; #define PG8_LDB(dst, b, h) do { _Pragma("unroll") for (int n = 0; n < 2; ++n) _Pragma("unroll") for (int k = 0; k < 2; ++k) dst[n][k] = *(const LAS bf16x8*)(lds + PG8_SB(b, h) + boff + n * 2048 + k * 1024); } while (0)
; #define PG8_MMA(ai, bj, At, Bt) do { __builtin_amdgcn_s_setprio(1); _Pragma("unroll") for (int m = 0; m < 4; ++m) _Pragma("unroll") for (int n = 0; n < 2; ++n) _Pragma("unroll") for (int k = 0; k < 2; ++k) \
;         acc[ai][bj][m][n] = __builtin_amdgcn_mfma_f32_16x16x32_bf16(Bt[n][k], At[m][k], acc[ai][bj][m][n], 0, 0, 0); __builtin_amdgcn_s_setprio(0); } while (0)
; #define PG8_WAIT_V(n) asm volatile("s_waitcnt vmcnt(" #n ")" ::: "memory")
; #define PG8_WAIT_L(n) asm volatile("s_waitcnt lgkmcnt(" #n ")" ::: "memory")
; #define PG8_BAR __builtin_amdgcn_s_barrier()
; #define PG8_SCHED __builtin_amdgcn_sched_barrier(0)
; template <class Epi, class SchedT, bool ALIGN_EPI, bool SP2>
; __device__ __forceinline__ void gemm_phase(LAS unsigned char* lds, const int ldk, const int nt, const SchedT& S, const Epi& E) {
;     ...
;             PG8_LDA(At, 0, 1); PG8_STAGE(PG8_SB(0, 0), b2, voffB); PG8_STAGE(PG8_SB(0, 1), b2 + hstepB, voffB); PG8_STAGE(PG8_SA(0, 0), a2, voffA);
;             PG8_WAIT_V(8); PG8_WAIT_L(0); PG8_BAR; PG8_MMA(1, 0, At, B0); PG8_MMA(1, 1, At, B1); PG8_BAR; PG8_SCHED;
;             PG8_LDB(B0, 1, 0); PG8_LDB(B1, 1, 1); PG8_SCHED; PG8_LDA(At, 1, 0); PG8_STAGE(PG8_SA(0, 1), a2 + hstep, voffA);
;             PG8_WAIT_V(8); PG8_WAIT_L(0); PG8_BAR; PG8_MMA(0, 0, At, B0); PG8_MMA(0, 1, At, B1); PG8_BAR; PG8_SCHED;
.Lg0w_p4_1:
	s_barrier
	s_setprio 1
	s_waitcnt lgkmcnt(0)
	v_mfma_f32_16x16x32_bf16 v[62:65], v[140:143], v[190:193], v[62:65]
	v_mfma_f32_16x16x32_bf16 v[58:61], v[154:157], v[190:193], v[58:61]
	v_mfma_f32_16x16x32_bf16 v[46:49], v[140:143], v[198:201], v[46:49]
	v_mfma_f32_16x16x32_bf16 v[42:45], v[154:157], v[198:201], v[42:45]
	v_mfma_f32_16x16x32_bf16 v[30:33], v[140:143], v[206:209], v[30:33]
	v_mfma_f32_16x16x32_bf16 v[26:29], v[154:157], v[206:209], v[26:29]
	v_mfma_f32_16x16x32_bf16 v[14:17], v[140:143], v[214:217], v[14:17]
	v_mfma_f32_16x16x32_bf16 v[10:13], v[154:157], v[214:217], v[10:13]
	v_mfma_f32_16x16x32_bf16 v[62:65], v[150:153], v[194:197], v[62:65]
	v_mfma_f32_16x16x32_bf16 v[58:61], v[158:161], v[194:197], v[58:61]
	v_mfma_f32_16x16x32_bf16 v[46:49], v[150:153], v[202:205], v[46:49]
	v_mfma_f32_16x16x32_bf16 v[42:45], v[158:161], v[202:205], v[42:45]
	v_mfma_f32_16x16x32_bf16 v[30:33], v[150:153], v[210:213], v[30:33]
	v_mfma_f32_16x16x32_bf16 v[26:29], v[158:161], v[210:213], v[26:29]
	v_mfma_f32_16x16x32_bf16 v[14:17], v[150:153], v[218:221], v[14:17]
	v_mfma_f32_16x16x32_bf16 v[10:13], v[158:161], v[218:221], v[10:13]
	s_setprio 0
	s_setprio 1
	v_mfma_f32_16x16x32_bf16 v[54:57], v[174:177], v[190:193], v[54:57]
	v_mfma_f32_16x16x32_bf16 v[50:53], v[182:185], v[190:193], v[50:53]
	v_mfma_f32_16x16x32_bf16 v[38:41], v[174:177], v[198:201], v[38:41]
	v_mfma_f32_16x16x32_bf16 v[34:37], v[182:185], v[198:201], v[34:37]
	v_mfma_f32_16x16x32_bf16 v[22:25], v[174:177], v[206:209], v[22:25]
	v_mfma_f32_16x16x32_bf16 v[18:21], v[182:185], v[206:209], v[18:21]
	v_mfma_f32_16x16x32_bf16 v[6:9], v[174:177], v[214:217], v[6:9]
	v_mfma_f32_16x16x32_bf16 v[2:5], v[182:185], v[214:217], v[2:5]
	v_mfma_f32_16x16x32_bf16 v[54:57], v[178:181], v[194:197], v[54:57]
	v_mfma_f32_16x16x32_bf16 v[50:53], v[186:189], v[194:197], v[50:53]
	v_mfma_f32_16x16x32_bf16 v[38:41], v[178:181], v[202:205], v[38:41]
	v_mfma_f32_16x16x32_bf16 v[34:37], v[186:189], v[202:205], v[34:37]
	v_mfma_f32_16x16x32_bf16 v[22:25], v[178:181], v[210:213], v[22:25]
	v_mfma_f32_16x16x32_bf16 v[18:21], v[186:189], v[210:213], v[18:21]
	v_mfma_f32_16x16x32_bf16 v[6:9], v[178:181], v[218:221], v[6:9]
	v_mfma_f32_16x16x32_bf16 v[2:5], v[186:189], v[218:221], v[2:5]
	s_setprio 0
	s_barrier
	s_add_i32 s51, 0, 0x18000
	s_add_i32 s53, 0, 0x1c000
	v_add_u32_e32 v158, s51, v147
	v_add_u32_e32 v186, s53, v147
	ds_read_b128 v[140:143], v158
	ds_read_b128 v[150:153], v158 offset:1024
	ds_read_b128 v[154:157], v158 offset:2048
	ds_read_b128 v[158:161], v158 offset:3072
	ds_read_b128 v[174:177], v186
	ds_read_b128 v[178:181], v186 offset:1024
	ds_read_b128 v[182:185], v186 offset:2048
	ds_read_b128 v[186:189], v186 offset:3072
	s_add_u32 s56, s56, 0x80000
	s_addc_u32 s57, s57, 0
	s_mov_b32 m0, s63
	v_lshl_add_u64 v[228:229], s[56:57], 0, v[130:131]
	ds_read_b128 v[190:193], v149 offset:32768
	ds_read_b128 v[194:197], v149 offset:33792
	ds_read_b128 v[198:201], v149 offset:34816
	ds_read_b128 v[202:205], v149 offset:35840
	ds_read_b128 v[206:209], v149 offset:36864
	ds_read_b128 v[210:213], v149 offset:37888
	ds_read_b128 v[214:217], v149 offset:38912
	ds_read_b128 v[218:221], v149 offset:39936
	global_load_lds_dwordx4 v[228:229], off
	v_lshl_add_u64 v[228:229], s[56:57], 0, v[132:133]
	s_mov_b32 m0, s81
	s_nop 0
	global_load_lds_dwordx4 v[228:229], off
	s_nop 0
	s_waitcnt vmcnt(8)
	s_cmp_lg_u64 s[48:49], 0
	s_cbranch_scc1 .Lg0w_p4_2
	s_waitcnt lgkmcnt(0)
.Lg0w_p4_2:
	s_barrier
	s_setprio 1
	s_waitcnt lgkmcnt(0)
	v_mfma_f32_16x16x32_bf16 v[126:129], v[140:143], v[190:193], v[126:129]
	v_mfma_f32_16x16x32_bf16 v[122:125], v[154:157], v[190:193], v[122:125]
	v_mfma_f32_16x16x32_bf16 v[110:113], v[140:143], v[198:201], v[110:113]
	v_mfma_f32_16x16x32_bf16 v[106:109], v[154:157], v[198:201], v[106:109]
	v_mfma_f32_16x16x32_bf16 v[94:97], v[140:143], v[206:209], v[94:97]
	v_mfma_f32_16x16x32_bf16 v[90:93], v[154:157], v[206:209], v[90:93]
	v_mfma_f32_16x16x32_bf16 v[78:81], v[140:143], v[214:217], v[78:81]
	v_mfma_f32_16x16x32_bf16 v[74:77], v[154:157], v[214:217], v[74:77]
	v_mfma_f32_16x16x32_bf16 v[126:129], v[150:153], v[194:197], v[126:129]
	v_mfma_f32_16x16x32_bf16 v[122:125], v[158:161], v[194:197], v[122:125]
	v_mfma_f32_16x16x32_bf16 v[110:113], v[150:153], v[202:205], v[110:113]
	v_mfma_f32_16x16x32_bf16 v[106:109], v[158:161], v[202:205], v[106:109]
	v_mfma_f32_16x16x32_bf16 v[94:97], v[150:153], v[210:213], v[94:97]
	v_mfma_f32_16x16x32_bf16 v[90:93], v[158:161], v[210:213], v[90:93]
	v_mfma_f32_16x16x32_bf16 v[78:81], v[150:153], v[218:221], v[78:81]
	v_mfma_f32_16x16x32_bf16 v[74:77], v[158:161], v[218:221], v[74:77]
	s_setprio 0
	s_setprio 1
	v_mfma_f32_16x16x32_bf16 v[118:121], v[174:177], v[190:193], v[118:121]
	v_mfma_f32_16x16x32_bf16 v[114:117], v[182:185], v[190:193], v[114:117]
	v_mfma_f32_16x16x32_bf16 v[102:105], v[174:177], v[198:201], v[102:105]
	v_mfma_f32_16x16x32_bf16 v[98:101], v[182:185], v[198:201], v[98:101]
	v_mfma_f32_16x16x32_bf16 v[86:89], v[174:177], v[206:209], v[86:89]
	v_mfma_f32_16x16x32_bf16 v[82:85], v[182:185], v[206:209], v[82:85]
	v_mfma_f32_16x16x32_bf16 v[70:73], v[174:177], v[214:217], v[70:73]
	v_mfma_f32_16x16x32_bf16 v[66:69], v[182:185], v[214:217], v[66:69]
	v_mfma_f32_16x16x32_bf16 v[118:121], v[178:181], v[194:197], v[118:121]
	v_mfma_f32_16x16x32_bf16 v[114:117], v[186:189], v[194:197], v[114:117]
	v_mfma_f32_16x16x32_bf16 v[102:105], v[178:181], v[202:205], v[102:105]
	v_mfma_f32_16x16x32_bf16 v[98:101], v[186:189], v[202:205], v[98:101]
	v_mfma_f32_16x16x32_bf16 v[86:89], v[178:181], v[210:213], v[86:89]
	v_mfma_f32_16x16x32_bf16 v[82:85], v[186:189], v[210:213], v[82:85]
	v_mfma_f32_16x16x32_bf16 v[70:73], v[178:181], v[218:221], v[70:73]
	v_mfma_f32_16x16x32_bf16 v[66:69], v[186:189], v[218:221], v[66:69]
	s_setprio 0
	s_barrier
; __device__ __forceinline__ float bf_lo(unsigned w) { return __uint_as_float(w << 16); }
; __device__ __forceinline__ float bf_hi(unsigned w) { return __uint_as_float(w & 0xffff0000u); }
; __device__ __forceinline__ u32x4 pack8(f32x4 a, f32x4 b) { u32x4 w; w.x = cvt_pk_bf16(a[0], a[1]); w.y = cvt_pk_bf16(a[2], a[3]); w.z = cvt_pk_bf16(b[0], b[1]); w.w = cvt_pk_bf16(b[2], b[3]); return w; }
; #define PG8_STAGE(bufoff, gbase, voff) do { _Pragma("unroll") for (int _i = 0; _i < 2; ++_i) \
;         __builtin_amdgcn_global_load_lds((const __attribute__((address_space(1))) unsigned*)((const char*)(gbase) + (voff)[_i]), (LAS unsigned*)(lds + (bufoff) + ldsw + _i * 8192), 16, 0, 0); } while (0)
; #define PG8_WAIT_V(n) asm volatile("s_waitcnt vmcnt(" #n ")" ::: "memory")
; template <class Epi, class SchedT, bool ALIGN_EPI, bool SP2>
; __device__ __forceinline__ void gemm_phase(LAS unsigned char* lds, const int ldk, const int nt, const SchedT& S, const Epi& E) {
;     ...
;             PG8_LDA(At, 1, 1); PG8_STAGE(PG8_SB(1, 0), b3, voffB); PG8_STAGE(PG8_SB(1, 1), b3 + hstepB, voffB); PG8_STAGE(PG8_SA(1, 0), a3, voffA);
;             PG8_WAIT_V(8); PG8_WAIT_L(0); PG8_BAR; PG8_MMA(1, 0, At, B0); PG8_MMA(1, 1, At, B1); PG8_BAR; PG8_SCHED;
;     __device__ __forceinline__ void operator()(f32x4 (&acc)[2][2][4][2], const Unit& u, int wr, int wc, int fr, int fq) const {
;         const int row0 = u.pm * BM + wr * 64 + fr, col0 = u.pn * BM + wc * 64 + 8 * fq;
; #pragma unroll
;         for (int ai = 0; ai < 2; ++ai)
; #pragma unroll
;             for (int m = 0; m < 4; ++m) {
;                 const int row = row0 + ai * HALF + m * 16; float sq = 0.f;
; #pragma unroll
;                 for (int bj = 0; bj < 2; ++bj) {
;                     const size_t off = (size_t)row * D + col0 + bj * 32;
;                     const u32x4 xw = *(const u32x4*)(xin + off);
;                     const f32x4 v0 = acc[ai][bj][m][0] + (f32x4){bf_lo(xw.x), bf_hi(xw.x), bf_lo(xw.y), bf_hi(xw.y)}, v1 = acc[ai][bj][m][1] + (f32x4){bf_lo(xw.z), bf_hi(xw.z), bf_lo(xw.w), bf_hi(xw.w)};
;                     *(u32x4*)(xb + off) = pack8(v0, v1);
;                     sq += (v0[0] * v0[0] + v0[1] * v0[1]) + (v0[2] * v0[2] + v0[3] * v0[3]) + (v1[0] * v1[0] + v1[1] * v1[1]) + (v1[2] * v1[2] + v1[3] * v1[3]);
;                 }
;                 sq += __shfl_xor(sq, 16); sq += __shfl_xor(sq, 32);
	s_add_i32 s51, s51, s61
	v_lshl_add_u64 v[144:145], v[144:145], 0, s[24:25]
	s_mov_b32 m0, s51
	ds_read_b128 v[190:193], v149 offset:49152
	ds_read_b128 v[194:197], v149 offset:50176
	ds_read_b128 v[198:201], v149 offset:51200
	ds_read_b128 v[202:205], v149 offset:52224
	ds_read_b128 v[206:209], v149 offset:53248
	ds_read_b128 v[210:213], v149 offset:54272
	ds_read_b128 v[214:217], v149 offset:55296
	ds_read_b128 v[218:221], v149 offset:56320
	global_load_lds_dwordx4 v[144:145], off
	s_add_i32 m0, s51, 0x2000
	s_add_u32 s36, s36, 0x20080
	v_lshl_add_u64 v[144:145], v[222:223], 0, s[24:25]
	s_addc_u32 s37, s37, 0
	s_add_i32 s51, s53, s61
	global_load_lds_dwordx4 v[144:145], off
	v_lshl_add_u64 v[144:145], s[36:37], 0, v[0:1]
	s_mov_b32 m0, s51
	s_nop 0
	global_load_lds_dwordx4 v[144:145], off
	v_lshl_add_u64 v[144:145], s[36:37], 0, v[134:135]
	s_add_i32 m0, s51, 0x2000
	s_nop 0
	global_load_lds_dwordx4 v[144:145], off
	v_lshl_add_u64 v[144:145], v[224:225], 0, s[24:25]
	s_mov_b32 m0, s83
	s_nop 0
	global_load_lds_dwordx4 v[144:145], off
	v_lshl_add_u64 v[144:145], v[226:227], 0, s[24:25]
	s_mov_b32 m0, s84
	s_nop 0
	global_load_lds_dwordx4 v[144:145], off
	s_waitcnt vmcnt(8)
	s_cmp_lg_u64 s[48:49], 0
	s_cbranch_scc1 .Lg0w_p4_3
	s_waitcnt lgkmcnt(0)
.Lg0w_p4_3:
	s_barrier
	s_setprio 1
	s_waitcnt lgkmcnt(0)
	v_mfma_f32_16x16x32_bf16 v[62:65], v[140:143], v[190:193], v[62:65]
	v_mfma_f32_16x16x32_bf16 v[58:61], v[154:157], v[190:193], v[58:61]
	v_mfma_f32_16x16x32_bf16 v[46:49], v[140:143], v[198:201], v[46:49]
	v_mfma_f32_16x16x32_bf16 v[42:45], v[154:157], v[198:201], v[42:45]
	v_mfma_f32_16x16x32_bf16 v[30:33], v[140:143], v[206:209], v[30:33]
	v_mfma_f32_16x16x32_bf16 v[26:29], v[154:157], v[206:209], v[26:29]
	v_mfma_f32_16x16x32_bf16 v[14:17], v[140:143], v[214:217], v[14:17]
	v_mfma_f32_16x16x32_bf16 v[10:13], v[154:157], v[214:217], v[10:13]
	v_mfma_f32_16x16x32_bf16 v[62:65], v[150:153], v[194:197], v[62:65]
	v_mfma_f32_16x16x32_bf16 v[58:61], v[158:161], v[194:197], v[58:61]
	v_mfma_f32_16x16x32_bf16 v[46:49], v[150:153], v[202:205], v[46:49]
	v_mfma_f32_16x16x32_bf16 v[42:45], v[158:161], v[202:205], v[42:45]
	v_mfma_f32_16x16x32_bf16 v[30:33], v[150:153], v[210:213], v[30:33]
	v_mfma_f32_16x16x32_bf16 v[26:29], v[158:161], v[210:213], v[26:29]
	v_mfma_f32_16x16x32_bf16 v[14:17], v[150:153], v[218:221], v[14:17]
	v_mfma_f32_16x16x32_bf16 v[10:13], v[158:161], v[218:221], v[10:13]
	s_setprio 0
	s_setprio 1
	v_mfma_f32_16x16x32_bf16 v[54:57], v[174:177], v[190:193], v[54:57]
	v_mfma_f32_16x16x32_bf16 v[50:53], v[182:185], v[190:193], v[50:53]
	v_mfma_f32_16x16x32_bf16 v[38:41], v[174:177], v[198:201], v[38:41]
	v_mfma_f32_16x16x32_bf16 v[34:37], v[182:185], v[198:201], v[34:37]
	v_mfma_f32_16x16x32_bf16 v[22:25], v[174:177], v[206:209], v[22:25]
	v_mfma_f32_16x16x32_bf16 v[18:21], v[182:185], v[206:209], v[18:21]
	v_mfma_f32_16x16x32_bf16 v[6:9], v[174:177], v[214:217], v[6:9]
	v_mfma_f32_16x16x32_bf16 v[2:5], v[182:185], v[214:217], v[2:5]
	v_mfma_f32_16x16x32_bf16 v[54:57], v[178:181], v[194:197], v[54:57]
	v_mfma_f32_16x16x32_bf16 v[50:53], v[186:189], v[194:197], v[50:53]
	v_mfma_f32_16x16x32_bf16 v[38:41], v[178:181], v[202:205], v[38:41]
	v_mfma_f32_16x16x32_bf16 v[34:37], v[186:189], v[202:205], v[34:37]
	v_mfma_f32_16x16x32_bf16 v[22:25], v[178:181], v[210:213], v[22:25]
	v_mfma_f32_16x16x32_bf16 v[18:21], v[186:189], v[210:213], v[18:21]
	v_mfma_f32_16x16x32_bf16 v[6:9], v[178:181], v[218:221], v[6:9]
	v_mfma_f32_16x16x32_bf16 v[2:5], v[186:189], v[218:221], v[2:5]
	s_setprio 0
	s_barrier
	s_add_i32 s22, s22, 2
	s_add_u32 s34, s34, 0x100
	s_addc_u32 s35, s35, 0
	s_add_u32 s13, s13, 0x100
	s_addc_u32 s20, s20, 0
	s_cmp_gt_u32 s22, 29
	s_cbranch_scc0 .LBB0_668
	v_lshl_add_u32 v142, s16, 8, v146
	v_lshl_or_b32 v140, s12, 8, v148
	v_lshlrev_b32_e32 v141, 12, v142
	v_lshl_add_u32 v150, v140, 1, v141
	v_add_u32_e32 v151, 0x10000, v150
	v_add_u32_e32 v152, 0x20000, v150
	v_add_u32_e32 v153, 0x30000, v150
	v_add_u32_e32 v154, 0x80000, v150
	v_add_u32_e32 v155, 0x90000, v150
	v_add_u32_e32 v156, 0xa0000, v150
	v_add_u32_e32 v157, 0xb0000, v150
	global_load_dwordx4 v[174:177], v150, s[42:43]
	global_load_dwordx4 v[178:181], v150, s[42:43] offset:64
	global_load_dwordx4 v[182:185], v151, s[42:43]
	global_load_dwordx4 v[186:189], v151, s[42:43] offset:64
	global_load_dwordx4 v[190:193], v152, s[42:43]
	global_load_dwordx4 v[194:197], v152, s[42:43] offset:64
	global_load_dwordx4 v[198:201], v153, s[42:43]
	global_load_dwordx4 v[202:205], v153, s[42:43] offset:64
	global_load_dwordx4 v[206:209], v154, s[42:43]
	global_load_dwordx4 v[210:213], v154, s[42:43] offset:64
	global_load_dwordx4 v[214:217], v155, s[42:43]
	global_load_dwordx4 v[218:221], v155, s[42:43] offset:64
	global_load_dwordx4 v[222:225], v156, s[42:43]
	global_load_dwordx4 v[226:229], v156, s[42:43] offset:64
	global_load_dwordx4 v[230:233], v157, s[42:43]
	global_load_dwordx4 v[234:237], v157, s[42:43] offset:64
	s_lshl_b32 s56, s12, 4
	s_lshl_b32 s22, s82, 2
	s_add_i32 s56, s56, s22
	v_lshl_add_u32 v158, v142, 7, s56
	v_add_u32_e32 v159, 0x1000, v158
	v_add_u32_e32 v160, 0x4000, v158
	v_add_u32_e32 v161, 0x5000, v158
	v_xor_b32_e32 v239, 16, v241
	v_xor_b32_e32 v252, 32, v241
	v_lshlrev_b32_e32 v239, 2, v239
	v_lshlrev_b32_e32 v252, 2, v252
	s_and_b64 vcc, exec, s[48:49]
	s_cbranch_vccz .LBB0_671
	s_barrier

; #define PG8_STAGE(bufoff, gbase, voff) do { _Pragma("unroll") for (int _i = 0; _i < 2; ++_i) \
;         __builtin_amdgcn_global_load_lds((const __attribute__((address_space(1))) unsigned*)((const char*)(gbase) + (voff)[_i]), (LAS unsigned*)(lds + (bufoff) + ldsw + _i * 8192), 16, 0, 0); } while (0)
; #define PG8_LDA(dst, b, h) do { _Pragma("unroll") for (int m = 0; m < 4; ++m) _Pragma("unroll") for (int k = 0; k < 2; ++k) dst[m][k] = *(const LAS bf16x8*)(lds + PG8_SA(b, h) + aoff + m * 2048 + k * 1024); } while (0)
; #define PG8_LDB(dst, b, h) do { _Pragma("unroll") for (int n = 0; n < 2; ++n) _Pragma("unroll") for (int k = 0; k < 2; ++k) dst[n][k] = *(const LAS bf16x8*)(lds + PG8_SB(b, h) + boff + n * 2048 + k * 1024); } while (0)
; #define PG8_MMA(ai, bj, At, Bt) do { __builtin_amdgcn_s_setprio(1); _Pragma("unroll") for (int m = 0; m < 4; ++m) _Pragma("unroll") for (int n = 0; n < 2; ++n) _Pragma("unroll") for (int k = 0; k < 2; ++k) \
;         acc[ai][bj][m][n] = __builtin_amdgcn_mfma_f32_16x16x32_bf16(Bt[n][k], At[m][k], acc[ai][bj][m][n], 0, 0, 0); __builtin_amdgcn_s_setprio(0); } while (0)
; #define PG8_WAIT_V(n) asm volatile("s_waitcnt vmcnt(" #n ")" ::: "memory")
; #define PG8_WAIT_L(n) asm volatile("s_waitcnt lgkmcnt(" #n ")" ::: "memory")
; #define PG8_BAR __builtin_amdgcn_s_barrier()
; template <class Epi, class SchedT, bool ALIGN_EPI, bool SP2>
; __device__ __forceinline__ void gemm_phase(LAS unsigned char* lds, const int ldk, const int nt, const SchedT& S, const Epi& E) {
;     ...
;             const bool last = (t == nt - 2);
;             const char* a1 = cA + (size_t)(t + 1) * kstep;
;             const char* a2 = last ? nA : cA + (size_t)(t + 2) * kstep; const char* b2 = last ? nB : cB + (size_t)(t + 2) * kstep;
;             const char* a3 = a2 + kstep; const char* b3 = b2 + kstep;
;             if constexpr (SP2) {
;             PG8_LDB(B0, 0, 0); PG8_LDB(B1, 0, 1); PG8_SCHED; PG8_LDA(At, 0, 0); PG8_STAGE(PG8_SA(1, 1), a1 + hstep, voffA);
;             PG8_WAIT_V(8); PG8_WAIT_L(0); PG8_BAR; PG8_MMA(0, 0, At, B0); PG8_MMA(0, 1, At, B1); PG8_BAR; PG8_SCHED;
;             PG8_LDA(At, 0, 1); PG8_STAGE(PG8_SB(0, 0), b2, voffB); PG8_STAGE(PG8_SB(0, 1), b2 + hstepB, voffB); PG8_STAGE(PG8_SA(0, 0), a2, voffA);
;             PG8_WAIT_V(8); PG8_WAIT_L(0); PG8_BAR; PG8_MMA(1, 0, At, B0); PG8_MMA(1, 1, At, B1); PG8_BAR; PG8_SCHED;
.LBB0_752:
	s_add_u32 s36, s34, 0xfff80080
	s_addc_u32 s37, s35, -1
	s_add_i32 s61, 0, 0x10000
	s_cmp_eq_u32 s59, 28
	s_cselect_b32 vcc_hi, s1, s37
	s_cselect_b32 vcc_lo, s0, s36
	s_cselect_b32 s37, s63, s17
	s_cselect_b32 s36, s62, s13
	s_add_i32 s64, 0, 0x14000
	v_add_u32_e32 v142, s61, v248
	v_add_u32_e32 v182, s64, v248
	ds_read_b128 v[130:133], v142
	ds_read_b128 v[134:137], v142 offset:1024
	ds_read_b128 v[138:141], v142 offset:2048
	ds_read_b128 v[142:145], v142 offset:3072
	ds_read_b128 v[158:161], v182
	ds_read_b128 v[174:177], v182 offset:1024
	ds_read_b128 v[178:181], v182 offset:2048
	ds_read_b128 v[182:185], v182 offset:3072
	v_lshl_add_u64 v[218:219], v[222:223], 0, s[24:25]
	s_mov_b32 m0, s89
	s_nop 0
	global_load_lds_dwordx4 v[218:219], off
	v_lshl_add_u64 v[218:219], v[224:225], 0, s[24:25]
	s_mov_b32 m0, s90
	s_nop 0
	global_load_lds_dwordx4 v[218:219], off
	v_lshl_add_u64 v[218:219], s[34:35], 0, v[154:155]
	s_add_i32 m0, s85, 0xc000
	ds_read_b128 v[186:189], v251
	ds_read_b128 v[190:193], v251 offset:1024
	ds_read_b128 v[194:197], v251 offset:2048
	ds_read_b128 v[198:201], v251 offset:3072
	ds_read_b128 v[202:205], v251 offset:4096
	ds_read_b128 v[206:209], v251 offset:5120
	ds_read_b128 v[210:213], v251 offset:6144
	ds_read_b128 v[214:217], v251 offset:7168
	global_load_lds_dwordx4 v[218:219], off
	v_lshl_add_u64 v[218:219], s[34:35], 0, v[156:157]
	s_add_i32 m0, s85, 0xe000
	s_nop 0
	global_load_lds_dwordx4 v[218:219], off
	s_nop 0
	s_nop 0
	s_nop 0
	s_waitcnt vmcnt(8)
	s_cmp_lg_u64 s[56:57], 0
	s_cbranch_scc1 .Lg0w_p5_0
	s_waitcnt lgkmcnt(0)
.Lg0w_p5_0:
	s_barrier
	s_setprio 1
	s_waitcnt lgkmcnt(0)
	v_mfma_f32_16x16x32_bf16 v[126:129], v[130:133], v[186:189], v[126:129]
	v_mfma_f32_16x16x32_bf16 v[62:65], v[138:141], v[186:189], v[62:65]
	v_mfma_f32_16x16x32_bf16 v[118:121], v[130:133], v[194:197], v[118:121]
	v_mfma_f32_16x16x32_bf16 v[58:61], v[138:141], v[194:197], v[58:61]
	v_mfma_f32_16x16x32_bf16 v[110:113], v[130:133], v[202:205], v[110:113]
	v_mfma_f32_16x16x32_bf16 v[46:49], v[138:141], v[202:205], v[46:49]
	v_mfma_f32_16x16x32_bf16 v[106:109], v[130:133], v[210:213], v[106:109]
	v_mfma_f32_16x16x32_bf16 v[42:45], v[138:141], v[210:213], v[42:45]
	v_mfma_f32_16x16x32_bf16 v[126:129], v[134:137], v[190:193], v[126:129]
	v_mfma_f32_16x16x32_bf16 v[62:65], v[142:145], v[190:193], v[62:65]
	v_mfma_f32_16x16x32_bf16 v[118:121], v[134:137], v[198:201], v[118:121]
	v_mfma_f32_16x16x32_bf16 v[58:61], v[142:145], v[198:201], v[58:61]
	v_mfma_f32_16x16x32_bf16 v[110:113], v[134:137], v[206:209], v[110:113]
	v_mfma_f32_16x16x32_bf16 v[46:49], v[142:145], v[206:209], v[46:49]
	v_mfma_f32_16x16x32_bf16 v[106:109], v[134:137], v[214:217], v[106:109]
	v_mfma_f32_16x16x32_bf16 v[42:45], v[142:145], v[214:217], v[42:45]
	s_setprio 0
	s_setprio 1
	v_mfma_f32_16x16x32_bf16 v[122:125], v[158:161], v[186:189], v[122:125]
	v_mfma_f32_16x16x32_bf16 v[54:57], v[178:181], v[186:189], v[54:57]
	v_mfma_f32_16x16x32_bf16 v[114:117], v[158:161], v[194:197], v[114:117]
	v_mfma_f32_16x16x32_bf16 v[50:53], v[178:181], v[194:197], v[50:53]
	v_mfma_f32_16x16x32_bf16 v[102:105], v[158:161], v[202:205], v[102:105]
	v_mfma_f32_16x16x32_bf16 v[38:41], v[178:181], v[202:205], v[38:41]
	v_mfma_f32_16x16x32_bf16 v[98:101], v[158:161], v[210:213], v[98:101]
	v_mfma_f32_16x16x32_bf16 v[34:37], v[178:181], v[210:213], v[34:37]
	v_mfma_f32_16x16x32_bf16 v[122:125], v[174:177], v[190:193], v[122:125]
	v_mfma_f32_16x16x32_bf16 v[54:57], v[182:185], v[190:193], v[54:57]
	v_mfma_f32_16x16x32_bf16 v[114:117], v[174:177], v[198:201], v[114:117]
	v_mfma_f32_16x16x32_bf16 v[50:53], v[182:185], v[198:201], v[50:53]
	v_mfma_f32_16x16x32_bf16 v[102:105], v[174:177], v[206:209], v[102:105]
	v_mfma_f32_16x16x32_bf16 v[38:41], v[182:185], v[206:209], v[38:41]
	v_mfma_f32_16x16x32_bf16 v[98:101], v[174:177], v[214:217], v[98:101]
	v_mfma_f32_16x16x32_bf16 v[34:37], v[182:185], v[214:217], v[34:37]
	s_setprio 0
	s_barrier
	s_add_i32 s61, s61, s84
	v_lshl_add_u64 v[218:219], s[36:37], 0, v[0:1]
	s_mov_b32 m0, s61
	ds_read_b128 v[186:189], v251 offset:16384
	ds_read_b128 v[190:193], v251 offset:17408
	ds_read_b128 v[194:197], v251 offset:18432
	ds_read_b128 v[198:201], v251 offset:19456
	ds_read_b128 v[202:205], v251 offset:20480
	ds_read_b128 v[206:209], v251 offset:21504
	ds_read_b128 v[210:213], v251 offset:22528
	ds_read_b128 v[214:217], v251 offset:23552
	global_load_lds_dwordx4 v[218:219], off
	s_add_i32 m0, s61, 0x2000
	s_add_u32 s94, s36, 0x20000
	v_lshl_add_u64 v[220:221], s[36:37], 0, v[150:151]
	s_addc_u32 s95, s37, 0
	s_add_i32 s61, s64, s84
	global_load_lds_dwordx4 v[220:221], off
	v_lshl_add_u64 v[222:223], s[94:95], 0, v[0:1]
	s_mov_b32 m0, s61
	v_lshl_add_u64 v[224:225], vcc, 0, v[148:149]
	global_load_lds_dwordx4 v[222:223], off
	v_lshl_add_u64 v[222:223], s[94:95], 0, v[150:151]
	s_add_i32 m0, s61, 0x2000
	s_nop 0
	global_load_lds_dwordx4 v[222:223], off
	v_lshl_add_u64 v[222:223], vcc, 0, v[146:147]
	s_nop 0
	s_waitcnt vmcnt(6)
	s_cmp_lg_u64 s[56:57], 0
	s_cbranch_scc1 .Lg0w_p5_1
	s_waitcnt lgkmcnt(0)
; #define PG8_STAGE(bufoff, gbase, voff) do { _Pragma("unroll") for (int _i = 0; _i < 2; ++_i) \
;         __builtin_amdgcn_global_load_lds((const __attribute__((address_space(1))) unsigned*)((const char*)(gbase) + (voff)[_i]), (LAS unsigned*)(lds + (bufoff) + ldsw + _i * 8192), 16, 0, 0); } while (0)
; #define PG8_LDA(dst, b, h) do { _Pragma("unroll") for (int m = 0; m < 4; ++m) _Pragma("unroll") for (int k = 0; k < 2; ++k) dst[m][k] = *(const LAS bf16x8*)(lds + PG8_SA(b, h) + aoff + m * 2048 + k * 1024); } while (0)
; #define PG8_LDB(dst, b, h) do { _Pragma("unroll") for (int n = 0; n < 2; ++n) _Pragma("unroll") for (int k = 0; k < 2; ++k) dst[n][k] = *(const LAS bf16x8*)(lds + PG8_SB(b, h) + boff + n * 2048 + k * 1024); } while (0)
; #define PG8_MMA(ai, bj, At, Bt) do { __builtin_amdgcn_s_setprio(1); _Pragma("unroll") for (int m = 0; m < 4; ++m) _Pragma("unroll") for (int n = 0; n < 2; ++n) _Pragma("unroll") for (int k = 0; k < 2; ++k) \
;         acc[ai][bj][m][n] = __builtin_amdgcn_mfma_f32_16x16x32_bf16(Bt[n][k], At[m][k], acc[ai][bj][m][n], 0, 0, 0); __builtin_amdgcn_s_setprio(0); } while (0)
; #define PG8_WAIT_V(n) asm volatile("s_waitcnt vmcnt(" #n ")" ::: "memory")
; #define PG8_WAIT_L(n) asm volatile("s_waitcnt lgkmcnt(" #n ")" ::: "memory")
; #define PG8_BAR __builtin_amdgcn_s_barrier()
; #define PG8_SCHED __builtin_amdgcn_sched_barrier(0)
; template <class Epi, class SchedT, bool ALIGN_EPI, bool SP2>
; __device__ __forceinline__ void gemm_phase(LAS unsigned char* lds, const int ldk, const int nt, const SchedT& S, const Epi& E) {
;     ...
;             PG8_LDA(At, 0, 1); PG8_STAGE(PG8_SB(0, 0), b2, voffB); PG8_STAGE(PG8_SB(0, 1), b2 + hstepB, voffB); PG8_STAGE(PG8_SA(0, 0), a2, voffA);
;             PG8_WAIT_V(8); PG8_WAIT_L(0); PG8_BAR; PG8_MMA(1, 0, At, B0); PG8_MMA(1, 1, At, B1); PG8_BAR; PG8_SCHED;
;             PG8_LDB(B0, 1, 0); PG8_LDB(B1, 1, 1); PG8_SCHED; PG8_LDA(At, 1, 0); PG8_STAGE(PG8_SA(0, 1), a2 + hstep, voffA);
;             PG8_WAIT_V(8); PG8_WAIT_L(0); PG8_BAR; PG8_MMA(0, 0, At, B0); PG8_MMA(0, 1, At, B1); PG8_BAR; PG8_SCHED;
.Lg0w_p5_1:
	s_barrier
	s_setprio 1
	s_waitcnt lgkmcnt(0)
	v_mfma_f32_16x16x32_bf16 v[94:97], v[130:133], v[186:189], v[94:97]
	v_mfma_f32_16x16x32_bf16 v[30:33], v[138:141], v[186:189], v[30:33]
	v_mfma_f32_16x16x32_bf16 v[90:93], v[130:133], v[194:197], v[90:93]
	v_mfma_f32_16x16x32_bf16 v[26:29], v[138:141], v[194:197], v[26:29]
	v_mfma_f32_16x16x32_bf16 v[78:81], v[130:133], v[202:205], v[78:81]
	v_mfma_f32_16x16x32_bf16 v[14:17], v[138:141], v[202:205], v[14:17]
	v_mfma_f32_16x16x32_bf16 v[74:77], v[130:133], v[210:213], v[74:77]
	v_mfma_f32_16x16x32_bf16 v[10:13], v[138:141], v[210:213], v[10:13]
	v_mfma_f32_16x16x32_bf16 v[94:97], v[134:137], v[190:193], v[94:97]
	v_mfma_f32_16x16x32_bf16 v[30:33], v[142:145], v[190:193], v[30:33]
	v_mfma_f32_16x16x32_bf16 v[90:93], v[134:137], v[198:201], v[90:93]
	v_mfma_f32_16x16x32_bf16 v[26:29], v[142:145], v[198:201], v[26:29]
	v_mfma_f32_16x16x32_bf16 v[78:81], v[134:137], v[206:209], v[78:81]
	v_mfma_f32_16x16x32_bf16 v[14:17], v[142:145], v[206:209], v[14:17]
	v_mfma_f32_16x16x32_bf16 v[74:77], v[134:137], v[214:217], v[74:77]
	v_mfma_f32_16x16x32_bf16 v[10:13], v[142:145], v[214:217], v[10:13]
	s_setprio 0
	s_setprio 1
	v_mfma_f32_16x16x32_bf16 v[86:89], v[158:161], v[186:189], v[86:89]
	v_mfma_f32_16x16x32_bf16 v[22:25], v[178:181], v[186:189], v[22:25]
	v_mfma_f32_16x16x32_bf16 v[82:85], v[158:161], v[194:197], v[82:85]
	v_mfma_f32_16x16x32_bf16 v[18:21], v[178:181], v[194:197], v[18:21]
	v_mfma_f32_16x16x32_bf16 v[70:73], v[158:161], v[202:205], v[70:73]
	v_mfma_f32_16x16x32_bf16 v[6:9], v[178:181], v[202:205], v[6:9]
	v_mfma_f32_16x16x32_bf16 v[66:69], v[158:161], v[210:213], v[66:69]
	v_mfma_f32_16x16x32_bf16 v[2:5], v[178:181], v[210:213], v[2:5]
	v_mfma_f32_16x16x32_bf16 v[86:89], v[174:177], v[190:193], v[86:89]
	v_mfma_f32_16x16x32_bf16 v[22:25], v[182:185], v[190:193], v[22:25]
	v_mfma_f32_16x16x32_bf16 v[82:85], v[174:177], v[198:201], v[82:85]
	v_mfma_f32_16x16x32_bf16 v[18:21], v[182:185], v[198:201], v[18:21]
	v_mfma_f32_16x16x32_bf16 v[70:73], v[174:177], v[206:209], v[70:73]
	v_mfma_f32_16x16x32_bf16 v[6:9], v[182:185], v[206:209], v[6:9]
	v_mfma_f32_16x16x32_bf16 v[66:69], v[174:177], v[214:217], v[66:69]
	v_mfma_f32_16x16x32_bf16 v[2:5], v[182:185], v[214:217], v[2:5]
	s_setprio 0
	s_barrier
	s_add_i32 s61, 0, 0x18000
	s_add_i32 s64, 0, 0x1c000
	v_add_u32_e32 v142, s61, v248
	v_add_u32_e32 v182, s64, v248
	ds_read_b128 v[130:133], v142
	ds_read_b128 v[134:137], v142 offset:1024
	ds_read_b128 v[138:141], v142 offset:2048
	ds_read_b128 v[142:145], v142 offset:3072
	ds_read_b128 v[158:161], v182
	ds_read_b128 v[174:177], v182 offset:1024
	ds_read_b128 v[178:181], v182 offset:2048
	ds_read_b128 v[182:185], v182 offset:3072
	s_add_u32 s94, vcc_lo, 0x80000
	s_addc_u32 s95, vcc_hi, 0
	s_mov_b32 m0, s85
	s_nop 0
	global_load_lds_dwordx4 v[222:223], off
	s_mov_b32 m0, s86
	s_nop 0
	global_load_lds_dwordx4 v[224:225], off
	s_mov_b32 m0, s87
	v_lshl_add_u64 v[226:227], s[94:95], 0, v[146:147]
	ds_read_b128 v[186:189], v251 offset:32768
	ds_read_b128 v[190:193], v251 offset:33792
	ds_read_b128 v[194:197], v251 offset:34816
	ds_read_b128 v[198:201], v251 offset:35840
	ds_read_b128 v[202:205], v251 offset:36864
	ds_read_b128 v[206:209], v251 offset:37888
	ds_read_b128 v[210:213], v251 offset:38912
	ds_read_b128 v[214:217], v251 offset:39936
	global_load_lds_dwordx4 v[226:227], off
	v_lshl_add_u64 v[226:227], s[94:95], 0, v[148:149]
	s_mov_b32 m0, s88
	s_nop 0
	global_load_lds_dwordx4 v[226:227], off
	s_nop 0
	s_waitcnt vmcnt(8)
	s_cmp_lg_u64 s[56:57], 0
	s_cbranch_scc1 .Lg0w_p5_2
	s_waitcnt lgkmcnt(0)
.Lg0w_p5_2:
	s_barrier
	s_setprio 1
	s_waitcnt lgkmcnt(0)
	v_mfma_f32_16x16x32_bf16 v[126:129], v[130:133], v[186:189], v[126:129]
	v_mfma_f32_16x16x32_bf16 v[62:65], v[138:141], v[186:189], v[62:65]
	v_mfma_f32_16x16x32_bf16 v[118:121], v[130:133], v[194:197], v[118:121]
	v_mfma_f32_16x16x32_bf16 v[58:61], v[138:141], v[194:197], v[58:61]
	v_mfma_f32_16x16x32_bf16 v[110:113], v[130:133], v[202:205], v[110:113]
	v_mfma_f32_16x16x32_bf16 v[46:49], v[138:141], v[202:205], v[46:49]
	v_mfma_f32_16x16x32_bf16 v[106:109], v[130:133], v[210:213], v[106:109]
	v_mfma_f32_16x16x32_bf16 v[42:45], v[138:141], v[210:213], v[42:45]
	v_mfma_f32_16x16x32_bf16 v[126:129], v[134:137], v[190:193], v[126:129]
	v_mfma_f32_16x16x32_bf16 v[62:65], v[142:145], v[190:193], v[62:65]
	v_mfma_f32_16x16x32_bf16 v[118:121], v[134:137], v[198:201], v[118:121]
	v_mfma_f32_16x16x32_bf16 v[58:61], v[142:145], v[198:201], v[58:61]
	v_mfma_f32_16x16x32_bf16 v[110:113], v[134:137], v[206:209], v[110:113]
	v_mfma_f32_16x16x32_bf16 v[46:49], v[142:145], v[206:209], v[46:49]
	v_mfma_f32_16x16x32_bf16 v[106:109], v[134:137], v[214:217], v[106:109]
	v_mfma_f32_16x16x32_bf16 v[42:45], v[142:145], v[214:217], v[42:45]
	s_setprio 0
	s_setprio 1
	v_mfma_f32_16x16x32_bf16 v[122:125], v[158:161], v[186:189], v[122:125]
	v_mfma_f32_16x16x32_bf16 v[54:57], v[178:181], v[186:189], v[54:57]
	v_mfma_f32_16x16x32_bf16 v[114:117], v[158:161], v[194:197], v[114:117]
	v_mfma_f32_16x16x32_bf16 v[50:53], v[178:181], v[194:197], v[50:53]
	v_mfma_f32_16x16x32_bf16 v[102:105], v[158:161], v[202:205], v[102:105]
	v_mfma_f32_16x16x32_bf16 v[38:41], v[178:181], v[202:205], v[38:41]
	v_mfma_f32_16x16x32_bf16 v[98:101], v[158:161], v[210:213], v[98:101]
	v_mfma_f32_16x16x32_bf16 v[34:37], v[178:181], v[210:213], v[34:37]
	v_mfma_f32_16x16x32_bf16 v[122:125], v[174:177], v[190:193], v[122:125]
	v_mfma_f32_16x16x32_bf16 v[54:57], v[182:185], v[190:193], v[54:57]
	v_mfma_f32_16x16x32_bf16 v[114:117], v[174:177], v[198:201], v[114:117]
	v_mfma_f32_16x16x32_bf16 v[50:53], v[182:185], v[198:201], v[50:53]
	v_mfma_f32_16x16x32_bf16 v[102:105], v[174:177], v[206:209], v[102:105]
	v_mfma_f32_16x16x32_bf16 v[38:41], v[182:185], v[206:209], v[38:41]
	v_mfma_f32_16x16x32_bf16 v[98:101], v[174:177], v[214:217], v[98:101]
	v_mfma_f32_16x16x32_bf16 v[34:37], v[182:185], v[214:217], v[34:37]
	s_setprio 0
	s_barrier
	s_add_i32 s61, s61, s84
	v_lshl_add_u64 v[218:219], v[218:219], 0, s[24:25]
	s_mov_b32 m0, s61
	ds_read_b128 v[186:189], v251 offset:49152
	ds_read_b128 v[190:193], v251 offset:50176
	ds_read_b128 v[194:197], v251 offset:51200
	ds_read_b128 v[198:201], v251 offset:52224
	ds_read_b128 v[202:205], v251 offset:53248
	ds_read_b128 v[206:209], v251 offset:54272
	ds_read_b128 v[210:213], v251 offset:55296
	ds_read_b128 v[214:217], v251 offset:56320
	global_load_lds_dwordx4 v[218:219], off
	s_add_i32 m0, s61, 0x2000
	s_add_u32 s36, s36, 0x20080
	v_lshl_add_u64 v[218:219], v[220:221], 0, s[24:25]
	s_addc_u32 s37, s37, 0
	s_add_i32 s61, s64, s84
	global_load_lds_dwordx4 v[218:219], off
	v_lshl_add_u64 v[218:219], s[36:37], 0, v[0:1]
	s_mov_b32 m0, s61
	s_nop 0
	global_load_lds_dwordx4 v[218:219], off
	v_lshl_add_u64 v[218:219], s[36:37], 0, v[150:151]
	s_add_i32 m0, s61, 0x2000
	s_nop 0
	global_load_lds_dwordx4 v[218:219], off
	s_waitcnt vmcnt(6)
	s_cmp_lg_u64 s[56:57], 0
	s_cbranch_scc1 .Lg0w_p5_3
	s_waitcnt lgkmcnt(0)
; #define PG8_STAGE(bufoff, gbase, voff) do { _Pragma("unroll") for (int _i = 0; _i < 2; ++_i) \
;         __builtin_amdgcn_global_load_lds((const __attribute__((address_space(1))) unsigned*)((const char*)(gbase) + (voff)[_i]), (LAS unsigned*)(lds + (bufoff) + ldsw + _i * 8192), 16, 0, 0); } while (0)
; #define PG8_LDA(dst, b, h) do { _Pragma("unroll") for (int m = 0; m < 4; ++m) _Pragma("unroll") for (int k = 0; k < 2; ++k) dst[m][k] = *(const LAS bf16x8*)(lds + PG8_SA(b, h) + aoff + m * 2048 + k * 1024); } while (0)
; #define PG8_MMA(ai, bj, At, Bt) do { __builtin_amdgcn_s_setprio(1); _Pragma("unroll") for (int m = 0; m < 4; ++m) _Pragma("unroll") for (int n = 0; n < 2; ++n) _Pragma("unroll") for (int k = 0; k < 2; ++k) \
;         acc[ai][bj][m][n] = __builtin_amdgcn_mfma_f32_16x16x32_bf16(Bt[n][k], At[m][k], acc[ai][bj][m][n], 0, 0, 0); __builtin_amdgcn_s_setprio(0); } while (0)
; #define PG8_WAIT_V(n) asm volatile("s_waitcnt vmcnt(" #n ")" ::: "memory")
; #define PG8_WAIT_L(n) asm volatile("s_waitcnt lgkmcnt(" #n ")" ::: "memory")
; #define PG8_BAR __builtin_amdgcn_s_barrier()
; #define PG8_SCHED __builtin_amdgcn_sched_barrier(0)
; __device__ __forceinline__ float row_rstd(const float* ssp, int row, int fq) {
;     const f32x4 a = *(const f32x4*)(ssp + (size_t)row * 32 + 8 * fq), b = *(const f32x4*)(ssp + (size_t)row * 32 + 8 * fq + 4);
;     float s = ((a[0] + a[1]) + (a[2] + a[3])) + ((b[0] + b[1]) + (b[2] + b[3]));
;     s += __shfl_xor(s, 16); s += __shfl_xor(s, 32);
; template <class Epi, class SchedT, bool ALIGN_EPI, bool SP2>
; __device__ __forceinline__ void gemm_phase(LAS unsigned char* lds, const int ldk, const int nt, const SchedT& S, const Epi& E) {
;     ...
;             PG8_LDA(At, 1, 1); PG8_STAGE(PG8_SB(1, 0), b3, voffB); PG8_STAGE(PG8_SB(1, 1), b3 + hstepB, voffB); PG8_STAGE(PG8_SA(1, 0), a3, voffA);
;             PG8_WAIT_V(8); PG8_WAIT_L(0); PG8_BAR; PG8_MMA(1, 0, At, B0); PG8_MMA(1, 1, At, B1); PG8_BAR; PG8_SCHED;
.Lg0w_p5_3:
	s_barrier
	s_setprio 1
	s_waitcnt lgkmcnt(0)
	v_mfma_f32_16x16x32_bf16 v[94:97], v[130:133], v[186:189], v[94:97]
	v_mfma_f32_16x16x32_bf16 v[30:33], v[138:141], v[186:189], v[30:33]
	v_mfma_f32_16x16x32_bf16 v[90:93], v[130:133], v[194:197], v[90:93]
	v_mfma_f32_16x16x32_bf16 v[26:29], v[138:141], v[194:197], v[26:29]
	v_mfma_f32_16x16x32_bf16 v[78:81], v[130:133], v[202:205], v[78:81]
	v_mfma_f32_16x16x32_bf16 v[14:17], v[138:141], v[202:205], v[14:17]
	v_mfma_f32_16x16x32_bf16 v[74:77], v[130:133], v[210:213], v[74:77]
	v_mfma_f32_16x16x32_bf16 v[10:13], v[138:141], v[210:213], v[10:13]
	v_mfma_f32_16x16x32_bf16 v[94:97], v[134:137], v[190:193], v[94:97]
	v_mfma_f32_16x16x32_bf16 v[30:33], v[142:145], v[190:193], v[30:33]
	v_mfma_f32_16x16x32_bf16 v[90:93], v[134:137], v[198:201], v[90:93]
	v_mfma_f32_16x16x32_bf16 v[26:29], v[142:145], v[198:201], v[26:29]
	v_mfma_f32_16x16x32_bf16 v[78:81], v[134:137], v[206:209], v[78:81]
	v_mfma_f32_16x16x32_bf16 v[14:17], v[142:145], v[206:209], v[14:17]
	v_mfma_f32_16x16x32_bf16 v[74:77], v[134:137], v[214:217], v[74:77]
	v_mfma_f32_16x16x32_bf16 v[10:13], v[142:145], v[214:217], v[10:13]
	s_setprio 0
	s_setprio 1
	v_mfma_f32_16x16x32_bf16 v[86:89], v[158:161], v[186:189], v[86:89]
	v_mfma_f32_16x16x32_bf16 v[22:25], v[178:181], v[186:189], v[22:25]
	v_mfma_f32_16x16x32_bf16 v[82:85], v[158:161], v[194:197], v[82:85]
	v_mfma_f32_16x16x32_bf16 v[18:21], v[178:181], v[194:197], v[18:21]
	v_mfma_f32_16x16x32_bf16 v[70:73], v[158:161], v[202:205], v[70:73]
	v_mfma_f32_16x16x32_bf16 v[6:9], v[178:181], v[202:205], v[6:9]
	v_mfma_f32_16x16x32_bf16 v[66:69], v[158:161], v[210:213], v[66:69]
	v_mfma_f32_16x16x32_bf16 v[2:5], v[178:181], v[210:213], v[2:5]
	v_mfma_f32_16x16x32_bf16 v[86:89], v[174:177], v[190:193], v[86:89]
	v_mfma_f32_16x16x32_bf16 v[22:25], v[182:185], v[190:193], v[22:25]
	v_mfma_f32_16x16x32_bf16 v[82:85], v[174:177], v[198:201], v[82:85]
	v_mfma_f32_16x16x32_bf16 v[18:21], v[182:185], v[198:201], v[18:21]
	v_mfma_f32_16x16x32_bf16 v[70:73], v[174:177], v[206:209], v[70:73]
	v_mfma_f32_16x16x32_bf16 v[6:9], v[182:185], v[206:209], v[6:9]
	v_mfma_f32_16x16x32_bf16 v[66:69], v[174:177], v[214:217], v[66:69]
	v_mfma_f32_16x16x32_bf16 v[2:5], v[182:185], v[214:217], v[2:5]
	s_setprio 0
	s_barrier
	s_add_i32 s59, s59, 2
	s_add_u32 s34, s34, 0x100
	s_addc_u32 s35, s35, 0
	s_add_u32 s13, s13, 0x100
	s_addc_u32 s17, s17, 0
	s_cmp_gt_u32 s59, 29
	s_cbranch_scc0 .LBB0_752
	v_lshl_add_u32 v130, s12, 8, v247
	v_lshlrev_b32_e32 v140, 7, v130
	v_mov_b32_e32 v141, 0
	v_lshl_add_u64 v[132:133], v[152:153], 0, v[140:141]
	v_add_u32_e32 v140, 0x1000, v140
	v_lshl_add_u64 v[134:135], v[152:153], 0, v[140:141]
	v_add_u32_e32 v140, 0x3000, v140
	v_lshl_add_u64 v[136:137], v[152:153], 0, v[140:141]
	v_add_u32_e32 v140, 0x1000, v140
	v_lshl_add_u64 v[138:139], v[152:153], 0, v[140:141]
	global_load_dwordx4 v[174:177], v[132:133], off
	global_load_dwordx4 v[178:181], v[132:133], off offset:16
	global_load_dwordx4 v[182:185], v[132:133], off offset:2048
	global_load_dwordx4 v[186:189], v[132:133], off offset:2064
	global_load_dwordx4 v[190:193], v[134:135], off
	global_load_dwordx4 v[194:197], v[134:135], off offset:16
	global_load_dwordx4 v[198:201], v[134:135], off offset:2048
	global_load_dwordx4 v[202:205], v[134:135], off offset:2064
	global_load_dwordx4 v[206:209], v[136:137], off
	global_load_dwordx4 v[210:213], v[136:137], off offset:16
	global_load_dwordx4 v[214:217], v[136:137], off offset:2048
	global_load_dwordx4 v[218:221], v[136:137], off offset:2064
	global_load_dwordx4 v[222:225], v[138:139], off
	global_load_dwordx4 v[226:229], v[138:139], off offset:16
	global_load_dwordx4 v[230:233], v[138:139], off offset:2048
	global_load_dwordx4 v[234:237], v[138:139], off offset:2064
	v_xor_b32_e32 v238, 16, v241
	v_xor_b32_e32 v239, 32, v241
	v_lshlrev_b32_e32 v238, 2, v238
	v_lshlrev_b32_e32 v239, 2, v239
	s_and_b64 vcc, exec, s[56:57]
	s_cbranch_vccz .LBB0_755
	s_barrier

; #define PG8_STAGE(bufoff, gbase, voff) do { _Pragma("unroll") for (int _i = 0; _i < 2; ++_i) \
;         __builtin_amdgcn_global_load_lds((const __attribute__((address_space(1))) unsigned*)((const char*)(gbase) + (voff)[_i]), (LAS unsigned*)(lds + (bufoff) + ldsw + _i * 8192), 16, 0, 0); } while (0)
; #define PG8_LDA(dst, b, h) do { _Pragma("unroll") for (int m = 0; m < 4; ++m) _Pragma("unroll") for (int k = 0; k < 2; ++k) dst[m][k] = *(const LAS bf16x8*)(lds + PG8_SA(b, h) + aoff + m * 2048 + k * 1024); } while (0)
; #define PG8_LDB(dst, b, h) do { _Pragma("unroll") for (int n = 0; n < 2; ++n) _Pragma("unroll") for (int k = 0; k < 2; ++k) dst[n][k] = *(const LAS bf16x8*)(lds + PG8_SB(b, h) + boff + n * 2048 + k * 1024); } while (0)
; #define PG8_MMA(ai, bj, At, Bt) do { __builtin_amdgcn_s_setprio(1); _Pragma("unroll") for (int m = 0; m < 4; ++m) _Pragma("unroll") for (int n = 0; n < 2; ++n) _Pragma("unroll") for (int k = 0; k < 2; ++k) \
;         acc[ai][bj][m][n] = __builtin_amdgcn_mfma_f32_16x16x32_bf16(Bt[n][k], At[m][k], acc[ai][bj][m][n], 0, 0, 0); __builtin_amdgcn_s_setprio(0); } while (0)
; #define PG8_WAIT_V(n) asm volatile("s_waitcnt vmcnt(" #n ")" ::: "memory")
; #define PG8_WAIT_L(n) asm volatile("s_waitcnt lgkmcnt(" #n ")" ::: "memory")
; #define PG8_BAR __builtin_amdgcn_s_barrier()
; template <class Epi, class SchedT, bool ALIGN_EPI, bool SP2>
; __device__ __forceinline__ void gemm_phase(LAS unsigned char* lds, const int ldk, const int nt, const SchedT& S, const Epi& E) {
;     ...
;             const bool last = (t == nt - 2);
;             const char* a1 = cA + (size_t)(t + 1) * kstep;
;             const char* a2 = last ? nA : cA + (size_t)(t + 2) * kstep; const char* b2 = last ? nB : cB + (size_t)(t + 2) * kstep;
;             const char* a3 = a2 + kstep; const char* b3 = b2 + kstep;
;             if constexpr (SP2) {
;             PG8_LDB(B0, 0, 0); PG8_LDB(B1, 0, 1); PG8_SCHED; PG8_LDA(At, 0, 0); PG8_STAGE(PG8_SA(1, 1), a1 + hstep, voffA);
;             PG8_WAIT_V(8); PG8_WAIT_L(0); PG8_BAR; PG8_MMA(0, 0, At, B0); PG8_MMA(0, 1, At, B1); PG8_BAR; PG8_SCHED;
;             PG8_LDA(At, 0, 1); PG8_STAGE(PG8_SB(0, 0), b2, voffB); PG8_STAGE(PG8_SB(0, 1), b2 + hstepB, voffB); PG8_STAGE(PG8_SA(0, 0), a2, voffA);
;             PG8_WAIT_V(8); PG8_WAIT_L(0); PG8_BAR; PG8_MMA(1, 0, At, B0); PG8_MMA(1, 1, At, B1); PG8_BAR; PG8_SCHED;
.LBB0_948:
	s_add_u32 s16, s12, 0x100
	s_addc_u32 s17, s13, 0
	s_add_i32 s64, 0, 0x10000
	s_cmpk_eq_i32 s83, 0x52
	s_cselect_b32 s47, s1, s17
	s_cselect_b32 s46, s0, s16
	v_add_u32_e32 v144, s64, v147
	s_cselect_b32 s45, s43, s82
	s_cselect_b32 s44, s42, s81
	s_add_i32 s65, 0, 0x14000
	ds_read_b128 v[140:143], v144
	ds_read_b128 v[150:153], v144 offset:1024
	ds_read_b128 v[154:157], v144 offset:2048
	ds_read_b128 v[158:161], v144 offset:3072
	v_add_u32_e32 v144, s65, v147
	ds_read_b128 v[174:177], v144
	ds_read_b128 v[178:181], v144 offset:1024
	ds_read_b128 v[182:185], v144 offset:2048
	ds_read_b128 v[186:189], v144 offset:3072
	v_lshl_add_u64 v[144:145], s[12:13], 0, v[136:137]
	s_add_i32 m0, s53, 0xc000
	ds_read_b128 v[190:193], v149
	ds_read_b128 v[194:197], v149 offset:1024
	ds_read_b128 v[198:201], v149 offset:2048
	ds_read_b128 v[202:205], v149 offset:3072
	ds_read_b128 v[206:209], v149 offset:4096
	ds_read_b128 v[210:213], v149 offset:5120
	ds_read_b128 v[214:217], v149 offset:6144
	ds_read_b128 v[218:221], v149 offset:7168
	global_load_lds_dwordx4 v[144:145], off
	v_lshl_add_u64 v[144:145], s[12:13], 0, v[138:139]
	s_add_i32 m0, s53, 0xe000
	s_nop 0
	global_load_lds_dwordx4 v[144:145], off
	s_nop 0
	s_nop 0
	s_nop 0
	s_nop 0
	s_nop 0
	s_waitcnt vmcnt(8)
	s_cmp_lg_u64 s[40:41], 0
	s_cbranch_scc1 .Lg0w_p7_0
	s_waitcnt lgkmcnt(0)
.Lg0w_p7_0:
	s_barrier
	s_setprio 1
	s_waitcnt lgkmcnt(0)
	v_mfma_f32_16x16x32_bf16 v[126:129], v[140:143], v[190:193], v[126:129]
	v_mfma_f32_16x16x32_bf16 v[122:125], v[154:157], v[190:193], v[122:125]
	v_mfma_f32_16x16x32_bf16 v[110:113], v[140:143], v[198:201], v[110:113]
	v_mfma_f32_16x16x32_bf16 v[106:109], v[154:157], v[198:201], v[106:109]
	v_mfma_f32_16x16x32_bf16 v[94:97], v[140:143], v[206:209], v[94:97]
	v_mfma_f32_16x16x32_bf16 v[90:93], v[154:157], v[206:209], v[90:93]
	v_mfma_f32_16x16x32_bf16 v[78:81], v[140:143], v[214:217], v[78:81]
	v_mfma_f32_16x16x32_bf16 v[74:77], v[154:157], v[214:217], v[74:77]
	v_mfma_f32_16x16x32_bf16 v[126:129], v[150:153], v[194:197], v[126:129]
	v_mfma_f32_16x16x32_bf16 v[122:125], v[158:161], v[194:197], v[122:125]
	v_mfma_f32_16x16x32_bf16 v[110:113], v[150:153], v[202:205], v[110:113]
	v_mfma_f32_16x16x32_bf16 v[106:109], v[158:161], v[202:205], v[106:109]
	v_mfma_f32_16x16x32_bf16 v[94:97], v[150:153], v[210:213], v[94:97]
	v_mfma_f32_16x16x32_bf16 v[90:93], v[158:161], v[210:213], v[90:93]
	v_mfma_f32_16x16x32_bf16 v[78:81], v[150:153], v[218:221], v[78:81]
	v_mfma_f32_16x16x32_bf16 v[74:77], v[158:161], v[218:221], v[74:77]
	s_setprio 0
	s_setprio 1
	v_mfma_f32_16x16x32_bf16 v[118:121], v[174:177], v[190:193], v[118:121]
	v_mfma_f32_16x16x32_bf16 v[114:117], v[182:185], v[190:193], v[114:117]
	v_mfma_f32_16x16x32_bf16 v[102:105], v[174:177], v[198:201], v[102:105]
	v_mfma_f32_16x16x32_bf16 v[98:101], v[182:185], v[198:201], v[98:101]
	v_mfma_f32_16x16x32_bf16 v[86:89], v[174:177], v[206:209], v[86:89]
	v_mfma_f32_16x16x32_bf16 v[82:85], v[182:185], v[206:209], v[82:85]
	v_mfma_f32_16x16x32_bf16 v[70:73], v[174:177], v[214:217], v[70:73]
	v_mfma_f32_16x16x32_bf16 v[66:69], v[182:185], v[214:217], v[66:69]
	v_mfma_f32_16x16x32_bf16 v[118:121], v[178:181], v[194:197], v[118:121]
	v_mfma_f32_16x16x32_bf16 v[114:117], v[186:189], v[194:197], v[114:117]
	v_mfma_f32_16x16x32_bf16 v[102:105], v[178:181], v[202:205], v[102:105]
	v_mfma_f32_16x16x32_bf16 v[98:101], v[186:189], v[202:205], v[98:101]
	v_mfma_f32_16x16x32_bf16 v[86:89], v[178:181], v[210:213], v[86:89]
	v_mfma_f32_16x16x32_bf16 v[82:85], v[186:189], v[210:213], v[82:85]
	v_mfma_f32_16x16x32_bf16 v[70:73], v[178:181], v[218:221], v[70:73]
	v_mfma_f32_16x16x32_bf16 v[66:69], v[186:189], v[218:221], v[66:69]
	s_setprio 0
	s_barrier
	s_add_i32 s12, s64, s52
	v_lshl_add_u64 v[144:145], s[44:45], 0, v[0:1]
	s_mov_b32 m0, s12
	ds_read_b128 v[190:193], v149 offset:16384
	ds_read_b128 v[194:197], v149 offset:17408
	ds_read_b128 v[198:201], v149 offset:18432
	ds_read_b128 v[202:205], v149 offset:19456
	ds_read_b128 v[206:209], v149 offset:20480
	ds_read_b128 v[210:213], v149 offset:21504
	ds_read_b128 v[214:217], v149 offset:22528
	ds_read_b128 v[218:221], v149 offset:23552
	global_load_lds_dwordx4 v[144:145], off
	s_add_i32 m0, s12, 0x2000
	s_add_u32 s12, s44, 0x56000
	v_lshl_add_u64 v[222:223], s[44:45], 0, v[134:135]
	s_addc_u32 s13, s45, 0
	s_add_i32 s64, s65, s52
	global_load_lds_dwordx4 v[222:223], off
	v_lshl_add_u64 v[224:225], s[12:13], 0, v[0:1]
	s_mov_b32 m0, s64
	v_lshl_add_u64 v[226:227], s[46:47], 0, v[132:133]
	global_load_lds_dwordx4 v[224:225], off
	v_lshl_add_u64 v[224:225], s[12:13], 0, v[134:135]
	s_add_i32 m0, s64, 0x2000
	s_nop 0
	global_load_lds_dwordx4 v[224:225], off
	v_lshl_add_u64 v[224:225], s[46:47], 0, v[130:131]
	s_mov_b32 m0, s53
	s_nop 0
	global_load_lds_dwordx4 v[224:225], off
	s_mov_b32 m0, s54
	s_nop 0
	global_load_lds_dwordx4 v[226:227], off
	s_nop 0
	s_waitcnt vmcnt(8)
	s_cmp_lg_u64 s[40:41], 0
	s_cbranch_scc1 .Lg0w_p7_1
	s_waitcnt lgkmcnt(0)
; #define PG8_STAGE(bufoff, gbase, voff) do { _Pragma("unroll") for (int _i = 0; _i < 2; ++_i) \
;         __builtin_amdgcn_global_load_lds((const __attribute__((address_space(1))) unsigned*)((const char*)(gbase) + (voff)[_i]), (LAS unsigned*)(lds + (bufoff) + ldsw + _i * 8192), 16, 0, 0); } while (0)
; #define PG8_LDA(dst, b, h) do { _Pragma("unroll") for (int m = 0; m < 4; ++m) _Pragma("unroll") for (int k = 0; k < 2; ++k) dst[m][k] = *(const LAS bf16x8*)(lds + PG8_SA(b, h) + aoff + m * 2048 + k * 1024); } while (0)
; #define PG8_LDB(dst, b, h) do { _Pragma("unroll") for (int n = 0; n < 2; ++n) _Pragma("unroll") for (int k = 0; k < 2; ++k) dst[n][k] = *(const LAS bf16x8*)(lds + PG8_SB(b, h) + boff + n * 2048 + k * 1024); } while (0)
; #define PG8_MMA(ai, bj, At, Bt) do { __builtin_amdgcn_s_setprio(1); _Pragma("unroll") for (int m = 0; m < 4; ++m) _Pragma("unroll") for (int n = 0; n < 2; ++n) _Pragma("unroll") for (int k = 0; k < 2; ++k) \
;         acc[ai][bj][m][n] = __builtin_amdgcn_mfma_f32_16x16x32_bf16(Bt[n][k], At[m][k], acc[ai][bj][m][n], 0, 0, 0); __builtin_amdgcn_s_setprio(0); } while (0)
; #define PG8_WAIT_V(n) asm volatile("s_waitcnt vmcnt(" #n ")" ::: "memory")
; #define PG8_WAIT_L(n) asm volatile("s_waitcnt lgkmcnt(" #n ")" ::: "memory")
; #define PG8_BAR __builtin_amdgcn_s_barrier()
; #define PG8_SCHED __builtin_amdgcn_sched_barrier(0)
; template <class Epi, class SchedT, bool ALIGN_EPI, bool SP2>
; __device__ __forceinline__ void gemm_phase(LAS unsigned char* lds, const int ldk, const int nt, const SchedT& S, const Epi& E) {
;     ...
;             PG8_LDA(At, 0, 1); PG8_STAGE(PG8_SB(0, 0), b2, voffB); PG8_STAGE(PG8_SB(0, 1), b2 + hstepB, voffB); PG8_STAGE(PG8_SA(0, 0), a2, voffA);
;             PG8_WAIT_V(8); PG8_WAIT_L(0); PG8_BAR; PG8_MMA(1, 0, At, B0); PG8_MMA(1, 1, At, B1); PG8_BAR; PG8_SCHED;
;             PG8_LDB(B0, 1, 0); PG8_LDB(B1, 1, 1); PG8_SCHED; PG8_LDA(At, 1, 0); PG8_STAGE(PG8_SA(0, 1), a2 + hstep, voffA);
;             PG8_WAIT_V(8); PG8_WAIT_L(0); PG8_BAR; PG8_MMA(0, 0, At, B0); PG8_MMA(0, 1, At, B1); PG8_BAR; PG8_SCHED;
.Lg0w_p7_1:
	s_barrier
	s_setprio 1
	s_waitcnt lgkmcnt(0)
	v_mfma_f32_16x16x32_bf16 v[62:65], v[140:143], v[190:193], v[62:65]
	v_mfma_f32_16x16x32_bf16 v[58:61], v[154:157], v[190:193], v[58:61]
	v_mfma_f32_16x16x32_bf16 v[46:49], v[140:143], v[198:201], v[46:49]
	v_mfma_f32_16x16x32_bf16 v[42:45], v[154:157], v[198:201], v[42:45]
	v_mfma_f32_16x16x32_bf16 v[30:33], v[140:143], v[206:209], v[30:33]
	v_mfma_f32_16x16x32_bf16 v[26:29], v[154:157], v[206:209], v[26:29]
	v_mfma_f32_16x16x32_bf16 v[14:17], v[140:143], v[214:217], v[14:17]
	v_mfma_f32_16x16x32_bf16 v[10:13], v[154:157], v[214:217], v[10:13]
	v_mfma_f32_16x16x32_bf16 v[62:65], v[150:153], v[194:197], v[62:65]
	v_mfma_f32_16x16x32_bf16 v[58:61], v[158:161], v[194:197], v[58:61]
	v_mfma_f32_16x16x32_bf16 v[46:49], v[150:153], v[202:205], v[46:49]
	v_mfma_f32_16x16x32_bf16 v[42:45], v[158:161], v[202:205], v[42:45]
	v_mfma_f32_16x16x32_bf16 v[30:33], v[150:153], v[210:213], v[30:33]
	v_mfma_f32_16x16x32_bf16 v[26:29], v[158:161], v[210:213], v[26:29]
	v_mfma_f32_16x16x32_bf16 v[14:17], v[150:153], v[218:221], v[14:17]
	v_mfma_f32_16x16x32_bf16 v[10:13], v[158:161], v[218:221], v[10:13]
	s_setprio 0
	s_setprio 1
	v_mfma_f32_16x16x32_bf16 v[54:57], v[174:177], v[190:193], v[54:57]
	v_mfma_f32_16x16x32_bf16 v[50:53], v[182:185], v[190:193], v[50:53]
	v_mfma_f32_16x16x32_bf16 v[38:41], v[174:177], v[198:201], v[38:41]
	v_mfma_f32_16x16x32_bf16 v[34:37], v[182:185], v[198:201], v[34:37]
	v_mfma_f32_16x16x32_bf16 v[22:25], v[174:177], v[206:209], v[22:25]
	v_mfma_f32_16x16x32_bf16 v[18:21], v[182:185], v[206:209], v[18:21]
	v_mfma_f32_16x16x32_bf16 v[6:9], v[174:177], v[214:217], v[6:9]
	v_mfma_f32_16x16x32_bf16 v[2:5], v[182:185], v[214:217], v[2:5]
	v_mfma_f32_16x16x32_bf16 v[54:57], v[178:181], v[194:197], v[54:57]
	v_mfma_f32_16x16x32_bf16 v[50:53], v[186:189], v[194:197], v[50:53]
	v_mfma_f32_16x16x32_bf16 v[38:41], v[178:181], v[202:205], v[38:41]
	v_mfma_f32_16x16x32_bf16 v[34:37], v[186:189], v[202:205], v[34:37]
	v_mfma_f32_16x16x32_bf16 v[22:25], v[178:181], v[210:213], v[22:25]
	v_mfma_f32_16x16x32_bf16 v[18:21], v[186:189], v[210:213], v[18:21]
	v_mfma_f32_16x16x32_bf16 v[6:9], v[178:181], v[218:221], v[6:9]
	v_mfma_f32_16x16x32_bf16 v[2:5], v[186:189], v[218:221], v[2:5]
	s_setprio 0
	s_barrier
	s_add_i32 s64, 0, 0x18000
	s_add_i32 s65, 0, 0x1c000
	v_add_u32_e32 v158, s64, v147
	v_add_u32_e32 v186, s65, v147
	ds_read_b128 v[140:143], v158
	ds_read_b128 v[150:153], v158 offset:1024
	ds_read_b128 v[154:157], v158 offset:2048
	ds_read_b128 v[158:161], v158 offset:3072
	ds_read_b128 v[174:177], v186
	ds_read_b128 v[178:181], v186 offset:1024
	ds_read_b128 v[182:185], v186 offset:2048
	ds_read_b128 v[186:189], v186 offset:3072
	s_add_u32 s12, s46, 0x158000
	s_addc_u32 s13, s47, 0
	s_mov_b32 m0, s55
	v_lshl_add_u64 v[228:229], s[12:13], 0, v[130:131]
	ds_read_b128 v[190:193], v149 offset:32768
	ds_read_b128 v[194:197], v149 offset:33792
	ds_read_b128 v[198:201], v149 offset:34816
	ds_read_b128 v[202:205], v149 offset:35840
	ds_read_b128 v[206:209], v149 offset:36864
	ds_read_b128 v[210:213], v149 offset:37888
	ds_read_b128 v[214:217], v149 offset:38912
	ds_read_b128 v[218:221], v149 offset:39936
	global_load_lds_dwordx4 v[228:229], off
	v_lshl_add_u64 v[228:229], s[12:13], 0, v[132:133]
	s_mov_b32 m0, s56
	s_nop 0
	global_load_lds_dwordx4 v[228:229], off
	s_nop 0
	s_waitcnt vmcnt(8)
	s_cmp_lg_u64 s[40:41], 0
	s_cbranch_scc1 .Lg0w_p7_2
	s_waitcnt lgkmcnt(0)
.Lg0w_p7_2:
	s_barrier
	s_setprio 1
	s_waitcnt lgkmcnt(0)
	v_mfma_f32_16x16x32_bf16 v[126:129], v[140:143], v[190:193], v[126:129]
	v_mfma_f32_16x16x32_bf16 v[122:125], v[154:157], v[190:193], v[122:125]
	v_mfma_f32_16x16x32_bf16 v[110:113], v[140:143], v[198:201], v[110:113]
	v_mfma_f32_16x16x32_bf16 v[106:109], v[154:157], v[198:201], v[106:109]
	v_mfma_f32_16x16x32_bf16 v[94:97], v[140:143], v[206:209], v[94:97]
	v_mfma_f32_16x16x32_bf16 v[90:93], v[154:157], v[206:209], v[90:93]
	v_mfma_f32_16x16x32_bf16 v[78:81], v[140:143], v[214:217], v[78:81]
	v_mfma_f32_16x16x32_bf16 v[74:77], v[154:157], v[214:217], v[74:77]
	v_mfma_f32_16x16x32_bf16 v[126:129], v[150:153], v[194:197], v[126:129]
	v_mfma_f32_16x16x32_bf16 v[122:125], v[158:161], v[194:197], v[122:125]
	v_mfma_f32_16x16x32_bf16 v[110:113], v[150:153], v[202:205], v[110:113]
	v_mfma_f32_16x16x32_bf16 v[106:109], v[158:161], v[202:205], v[106:109]
	v_mfma_f32_16x16x32_bf16 v[94:97], v[150:153], v[210:213], v[94:97]
	v_mfma_f32_16x16x32_bf16 v[90:93], v[158:161], v[210:213], v[90:93]
	v_mfma_f32_16x16x32_bf16 v[78:81], v[150:153], v[218:221], v[78:81]
	v_mfma_f32_16x16x32_bf16 v[74:77], v[158:161], v[218:221], v[74:77]
	s_setprio 0
	s_setprio 1
	v_mfma_f32_16x16x32_bf16 v[118:121], v[174:177], v[190:193], v[118:121]
	v_mfma_f32_16x16x32_bf16 v[114:117], v[182:185], v[190:193], v[114:117]
	v_mfma_f32_16x16x32_bf16 v[102:105], v[174:177], v[198:201], v[102:105]
	v_mfma_f32_16x16x32_bf16 v[98:101], v[182:185], v[198:201], v[98:101]
	v_mfma_f32_16x16x32_bf16 v[86:89], v[174:177], v[206:209], v[86:89]
	v_mfma_f32_16x16x32_bf16 v[82:85], v[182:185], v[206:209], v[82:85]
	v_mfma_f32_16x16x32_bf16 v[70:73], v[174:177], v[214:217], v[70:73]
	v_mfma_f32_16x16x32_bf16 v[66:69], v[182:185], v[214:217], v[66:69]
	v_mfma_f32_16x16x32_bf16 v[118:121], v[178:181], v[194:197], v[118:121]
	v_mfma_f32_16x16x32_bf16 v[114:117], v[186:189], v[194:197], v[114:117]
	v_mfma_f32_16x16x32_bf16 v[102:105], v[178:181], v[202:205], v[102:105]
	v_mfma_f32_16x16x32_bf16 v[98:101], v[186:189], v[202:205], v[98:101]
	v_mfma_f32_16x16x32_bf16 v[86:89], v[178:181], v[210:213], v[86:89]
	v_mfma_f32_16x16x32_bf16 v[82:85], v[186:189], v[210:213], v[82:85]
	v_mfma_f32_16x16x32_bf16 v[70:73], v[178:181], v[218:221], v[70:73]
	v_mfma_f32_16x16x32_bf16 v[66:69], v[186:189], v[218:221], v[66:69]
	s_setprio 0
	s_barrier
; __device__ __forceinline__ float bf_lo(unsigned w) { return __uint_as_float(w << 16); }
; __device__ __forceinline__ float bf_hi(unsigned w) { return __uint_as_float(w & 0xffff0000u); }
; __device__ __forceinline__ u32x4 pack8(f32x4 a, f32x4 b) { u32x4 w; w.x = cvt_pk_bf16(a[0], a[1]); w.y = cvt_pk_bf16(a[2], a[3]); w.z = cvt_pk_bf16(b[0], b[1]); w.w = cvt_pk_bf16(b[2], b[3]); return w; }
; #define PG8_STAGE(bufoff, gbase, voff) do { _Pragma("unroll") for (int _i = 0; _i < 2; ++_i) \
;         __builtin_amdgcn_global_load_lds((const __attribute__((address_space(1))) unsigned*)((const char*)(gbase) + (voff)[_i]), (LAS unsigned*)(lds + (bufoff) + ldsw + _i * 8192), 16, 0, 0); } while (0)
; #define PG8_WAIT_V(n) asm volatile("s_waitcnt vmcnt(" #n ")" ::: "memory")
; template <class Epi, class SchedT, bool ALIGN_EPI, bool SP2>
; __device__ __forceinline__ void gemm_phase(LAS unsigned char* lds, const int ldk, const int nt, const SchedT& S, const Epi& E) {
;     ...
;             PG8_LDA(At, 1, 1); PG8_STAGE(PG8_SB(1, 0), b3, voffB); PG8_STAGE(PG8_SB(1, 1), b3 + hstepB, voffB); PG8_STAGE(PG8_SA(1, 0), a3, voffA);
;             PG8_WAIT_V(8); PG8_WAIT_L(0); PG8_BAR; PG8_MMA(1, 0, At, B0); PG8_MMA(1, 1, At, B1); PG8_BAR; PG8_SCHED;
;     __device__ __forceinline__ void operator()(f32x4 (&acc)[2][2][4][2], const Unit& u, int wr, int wc, int fr, int fq) const {
;         const int row0 = u.pm * BM + wr * 64 + fr, col0 = u.pn * BM + wc * 64 + 8 * fq;
; #pragma unroll
;         for (int ai = 0; ai < 2; ++ai)
; #pragma unroll
;             for (int m = 0; m < 4; ++m) {
;                 const int row = row0 + ai * HALF + m * 16; float sq = 0.f;
; #pragma unroll
;                 for (int bj = 0; bj < 2; ++bj) {
;                     const size_t off = (size_t)row * D + col0 + bj * 32;
;                     const u32x4 xw = *(const u32x4*)(xin + off);
;                     const f32x4 v0 = acc[ai][bj][m][0] + (f32x4){bf_lo(xw.x), bf_hi(xw.x), bf_lo(xw.y), bf_hi(xw.y)}, v1 = acc[ai][bj][m][1] + (f32x4){bf_lo(xw.z), bf_hi(xw.z), bf_lo(xw.w), bf_hi(xw.w)};
;                     *(u32x4*)(xb + off) = pack8(v0, v1);
;                     sq += (v0[0] * v0[0] + v0[1] * v0[1]) + (v0[2] * v0[2] + v0[3] * v0[3]) + (v1[0] * v1[0] + v1[1] * v1[1]) + (v1[2] * v1[2] + v1[3] * v1[3]);
;                 }
;                 sq += __shfl_xor(sq, 16); sq += __shfl_xor(sq, 32);
	s_add_i32 s12, s64, s52
	v_lshl_add_u64 v[144:145], v[144:145], 0, s[24:25]
	s_mov_b32 m0, s12
	ds_read_b128 v[190:193], v149 offset:49152
	ds_read_b128 v[194:197], v149 offset:50176
	ds_read_b128 v[198:201], v149 offset:51200
	ds_read_b128 v[202:205], v149 offset:52224
	ds_read_b128 v[206:209], v149 offset:53248
	ds_read_b128 v[210:213], v149 offset:54272
	ds_read_b128 v[214:217], v149 offset:55296
	ds_read_b128 v[218:221], v149 offset:56320
	global_load_lds_dwordx4 v[144:145], off
	s_add_i32 m0, s12, 0x2000
	s_add_u32 s12, s44, 0x56080
	v_lshl_add_u64 v[144:145], v[222:223], 0, s[24:25]
	s_addc_u32 s13, s45, 0
	s_add_i32 s44, s65, s52
	global_load_lds_dwordx4 v[144:145], off
	v_lshl_add_u64 v[144:145], s[12:13], 0, v[0:1]
	s_mov_b32 m0, s44
	s_nop 0
	global_load_lds_dwordx4 v[144:145], off
	v_lshl_add_u64 v[144:145], s[12:13], 0, v[134:135]
	s_add_i32 m0, s44, 0x2000
	s_nop 0
	global_load_lds_dwordx4 v[144:145], off
	v_lshl_add_u64 v[144:145], v[224:225], 0, s[24:25]
	s_mov_b32 m0, s58
	s_nop 0
	global_load_lds_dwordx4 v[144:145], off
	v_lshl_add_u64 v[144:145], v[226:227], 0, s[24:25]
	s_mov_b32 m0, s59
	s_nop 0
	global_load_lds_dwordx4 v[144:145], off
	s_waitcnt vmcnt(8)
	s_cmp_lg_u64 s[40:41], 0
	s_cbranch_scc1 .Lg0w_p7_3
	s_waitcnt lgkmcnt(0)
.Lg0w_p7_3:
	s_barrier
	s_setprio 1
	s_waitcnt lgkmcnt(0)
	v_mfma_f32_16x16x32_bf16 v[62:65], v[140:143], v[190:193], v[62:65]
	v_mfma_f32_16x16x32_bf16 v[58:61], v[154:157], v[190:193], v[58:61]
	v_mfma_f32_16x16x32_bf16 v[46:49], v[140:143], v[198:201], v[46:49]
	v_mfma_f32_16x16x32_bf16 v[42:45], v[154:157], v[198:201], v[42:45]
	v_mfma_f32_16x16x32_bf16 v[30:33], v[140:143], v[206:209], v[30:33]
	v_mfma_f32_16x16x32_bf16 v[26:29], v[154:157], v[206:209], v[26:29]
	v_mfma_f32_16x16x32_bf16 v[14:17], v[140:143], v[214:217], v[14:17]
	v_mfma_f32_16x16x32_bf16 v[10:13], v[154:157], v[214:217], v[10:13]
	v_mfma_f32_16x16x32_bf16 v[62:65], v[150:153], v[194:197], v[62:65]
	v_mfma_f32_16x16x32_bf16 v[58:61], v[158:161], v[194:197], v[58:61]
	v_mfma_f32_16x16x32_bf16 v[46:49], v[150:153], v[202:205], v[46:49]
	v_mfma_f32_16x16x32_bf16 v[42:45], v[158:161], v[202:205], v[42:45]
	v_mfma_f32_16x16x32_bf16 v[30:33], v[150:153], v[210:213], v[30:33]
	v_mfma_f32_16x16x32_bf16 v[26:29], v[158:161], v[210:213], v[26:29]
	v_mfma_f32_16x16x32_bf16 v[14:17], v[150:153], v[218:221], v[14:17]
	v_mfma_f32_16x16x32_bf16 v[10:13], v[158:161], v[218:221], v[10:13]
	s_setprio 0
	s_setprio 1
	v_mfma_f32_16x16x32_bf16 v[54:57], v[174:177], v[190:193], v[54:57]
	v_mfma_f32_16x16x32_bf16 v[50:53], v[182:185], v[190:193], v[50:53]
	v_mfma_f32_16x16x32_bf16 v[38:41], v[174:177], v[198:201], v[38:41]
	v_mfma_f32_16x16x32_bf16 v[34:37], v[182:185], v[198:201], v[34:37]
	v_mfma_f32_16x16x32_bf16 v[22:25], v[174:177], v[206:209], v[22:25]
	v_mfma_f32_16x16x32_bf16 v[18:21], v[182:185], v[206:209], v[18:21]
	v_mfma_f32_16x16x32_bf16 v[6:9], v[174:177], v[214:217], v[6:9]
	v_mfma_f32_16x16x32_bf16 v[2:5], v[182:185], v[214:217], v[2:5]
	v_mfma_f32_16x16x32_bf16 v[54:57], v[178:181], v[194:197], v[54:57]
	v_mfma_f32_16x16x32_bf16 v[50:53], v[186:189], v[194:197], v[50:53]
	v_mfma_f32_16x16x32_bf16 v[38:41], v[178:181], v[202:205], v[38:41]
	v_mfma_f32_16x16x32_bf16 v[34:37], v[186:189], v[202:205], v[34:37]
	v_mfma_f32_16x16x32_bf16 v[22:25], v[178:181], v[210:213], v[22:25]
	v_mfma_f32_16x16x32_bf16 v[18:21], v[186:189], v[210:213], v[18:21]
	v_mfma_f32_16x16x32_bf16 v[6:9], v[178:181], v[218:221], v[6:9]
	v_mfma_f32_16x16x32_bf16 v[2:5], v[186:189], v[218:221], v[2:5]
	s_setprio 0
	s_barrier
	s_add_i32 s83, s83, 2
	s_add_u32 s81, s81, 0x100
	s_addc_u32 s82, s82, 0
	s_cmpk_gt_u32 s83, 0x53
	s_mov_b64 s[12:13], s[16:17]
	s_cbranch_scc0 .LBB0_948
	v_lshl_add_u32 v142, s63, 8, v146
	v_lshl_or_b32 v140, s22, 8, v148
	v_lshlrev_b32_e32 v141, 12, v142
	v_lshl_add_u32 v150, v140, 1, v141
	v_add_u32_e32 v151, 0x10000, v150
	v_add_u32_e32 v152, 0x20000, v150
	v_add_u32_e32 v153, 0x30000, v150
	v_add_u32_e32 v154, 0x80000, v150
	v_add_u32_e32 v155, 0x90000, v150
	v_add_u32_e32 v156, 0xa0000, v150
	v_add_u32_e32 v157, 0xb0000, v150
	global_load_dwordx4 v[174:177], v150, s[20:21]
	global_load_dwordx4 v[178:181], v150, s[20:21] offset:64
	global_load_dwordx4 v[182:185], v151, s[20:21]
	global_load_dwordx4 v[186:189], v151, s[20:21] offset:64
	global_load_dwordx4 v[190:193], v152, s[20:21]
	global_load_dwordx4 v[194:197], v152, s[20:21] offset:64
	global_load_dwordx4 v[198:201], v153, s[20:21]
	global_load_dwordx4 v[202:205], v153, s[20:21] offset:64
	global_load_dwordx4 v[206:209], v154, s[20:21]
	global_load_dwordx4 v[210:213], v154, s[20:21] offset:64
	global_load_dwordx4 v[214:217], v155, s[20:21]
	global_load_dwordx4 v[218:221], v155, s[20:21] offset:64
	global_load_dwordx4 v[222:225], v156, s[20:21]
	global_load_dwordx4 v[226:229], v156, s[20:21] offset:64
	global_load_dwordx4 v[230:233], v157, s[20:21]
	global_load_dwordx4 v[234:237], v157, s[20:21] offset:64
	s_lshl_b32 s44, s22, 4
	s_lshl_b32 s45, s57, 2
	s_add_i32 s44, s44, s45
	v_lshl_add_u32 v158, v142, 7, s44
	v_add_u32_e32 v159, 0x1000, v158
	v_add_u32_e32 v160, 0x4000, v158
	v_add_u32_e32 v161, 0x5000, v158
	v_xor_b32_e32 v239, 16, v241
	v_xor_b32_e32 v252, 32, v241
	v_lshlrev_b32_e32 v239, 2, v239
	v_lshlrev_b32_e32 v252, 2, v252
	s_and_b64 vcc, exec, s[40:41]
	s_cbranch_vccz .LBB0_951
	s_barrier
